# epilogue re-alignment of the two wave groups extended to P3 and P4 (concurrent epilogues in P1,P3,P4,P7)
# baseline (speedup 1.0000x reference)
.LBB0_167:
	s_cmpk_lt_u32 s51, 0x100
	s_cbranch_scc1 .Lep_b_175
	s_barrier

.LBB0_175:
	s_add_i32 s26, s27, 2
	s_add_u32 s44, s40, 0x100
	s_addc_u32 s45, s41, 0
	s_add_i32 s30, 0, 0x10000
	ds_read_b128 v[132:135], v1
	ds_read_b128 v[164:167], v1 offset:1024
	ds_read_b128 v[168:171], v1 offset:2048
	ds_read_b128 v[174:177], v1 offset:3072
	s_cmp_eq_u32 s23, s27
	s_cselect_b32 s49, s1, s45
	s_cselect_b32 s48, s0, s44
	s_cselect_b32 s47, s43, s25
	s_cselect_b32 s46, s42, s24
	s_add_i32 m0, s53, 0xc000
	ds_read_b128 v[178:181], v172
	ds_read_b128 v[182:185], v172 offset:1024
	ds_read_b128 v[186:189], v172 offset:2048
	ds_read_b128 v[190:193], v172 offset:3072
	ds_read_b128 v[202:205], v172 offset:4096
	ds_read_b128 v[206:209], v172 offset:5120
	ds_read_b128 v[210:213], v172 offset:6144
	global_load_lds_dwordx4 v160, s[40:41]
	s_add_i32 m0, s53, 0xe000
	ds_read_b128 v[214:217], v172 offset:7168
	global_load_lds_dwordx4 v162, s[40:41]
	s_waitcnt lgkmcnt(8)
	s_barrier
	s_waitcnt lgkmcnt(0)
	v_mfma_f32_16x16x32_bf16 v[4:7], v[132:135], v[178:181], v[4:7]
	v_mfma_f32_16x16x32_bf16 v[8:11], v[168:171], v[178:181], v[8:11]
	v_mfma_f32_16x16x32_bf16 v[128:131], v[132:135], v[186:189], v[128:131]
	v_mfma_f32_16x16x32_bf16 v[124:127], v[168:171], v[186:189], v[124:127]
	v_mfma_f32_16x16x32_bf16 v[120:123], v[132:135], v[202:205], v[120:123]
	v_mfma_f32_16x16x32_bf16 v[116:119], v[168:171], v[202:205], v[116:119]
	v_mfma_f32_16x16x32_bf16 v[112:115], v[132:135], v[210:213], v[112:115]
	v_mfma_f32_16x16x32_bf16 v[108:111], v[168:171], v[210:213], v[108:111]
	v_mfma_f32_16x16x32_bf16 v[4:7], v[164:167], v[182:185], v[4:7]
	v_mfma_f32_16x16x32_bf16 v[8:11], v[174:177], v[182:185], v[8:11]
	v_mfma_f32_16x16x32_bf16 v[128:131], v[164:167], v[190:193], v[128:131]
	v_mfma_f32_16x16x32_bf16 v[124:127], v[174:177], v[190:193], v[124:127]
	v_mfma_f32_16x16x32_bf16 v[120:123], v[164:167], v[206:209], v[120:123]
	v_mfma_f32_16x16x32_bf16 v[116:119], v[174:177], v[206:209], v[116:119]
	v_mfma_f32_16x16x32_bf16 v[112:115], v[164:167], v[214:217], v[112:115]
	v_mfma_f32_16x16x32_bf16 v[108:111], v[174:177], v[214:217], v[108:111]
	s_barrier
	s_add_i32 s27, 0, 0x14000
	s_add_i32 s30, s30, s52
	ds_read_b128 v[236:239], v1 offset:16384
	ds_read_b128 v[240:243], v1 offset:17408
	s_mov_b32 m0, s30
	ds_read_b128 v[244:247], v1 offset:18432
	global_load_lds_dwordx4 v138, s[46:47]
	s_add_i32 m0, s30, 0x2000
	ds_read_b128 v[248:251], v1 offset:19456
	global_load_lds_dwordx4 v142, s[46:47]
	s_barrier
	s_waitcnt lgkmcnt(0)
	v_mfma_f32_16x16x32_bf16 v[12:15], v[236:239], v[178:181], v[12:15]
	v_mfma_f32_16x16x32_bf16 v[16:19], v[244:247], v[178:181], v[16:19]
	v_mfma_f32_16x16x32_bf16 v[104:107], v[236:239], v[186:189], v[104:107]
	v_mfma_f32_16x16x32_bf16 v[100:103], v[244:247], v[186:189], v[100:103]
	v_mfma_f32_16x16x32_bf16 v[96:99], v[236:239], v[202:205], v[96:99]
	v_mfma_f32_16x16x32_bf16 v[92:95], v[244:247], v[202:205], v[92:95]
	v_mfma_f32_16x16x32_bf16 v[88:91], v[236:239], v[210:213], v[88:91]
	v_mfma_f32_16x16x32_bf16 v[84:87], v[244:247], v[210:213], v[84:87]
	v_mfma_f32_16x16x32_bf16 v[12:15], v[240:243], v[182:185], v[12:15]
	v_mfma_f32_16x16x32_bf16 v[16:19], v[248:251], v[182:185], v[16:19]
	v_mfma_f32_16x16x32_bf16 v[104:107], v[240:243], v[190:193], v[104:107]
	v_mfma_f32_16x16x32_bf16 v[100:103], v[248:251], v[190:193], v[100:103]
	v_mfma_f32_16x16x32_bf16 v[96:99], v[240:243], v[206:209], v[96:99]
	v_mfma_f32_16x16x32_bf16 v[92:95], v[248:251], v[206:209], v[92:95]
	v_mfma_f32_16x16x32_bf16 v[88:91], v[240:243], v[214:217], v[88:91]
	v_mfma_f32_16x16x32_bf16 v[84:87], v[248:251], v[214:217], v[84:87]
	s_mov_b32 m0, s53
	s_barrier
	ds_read_b128 v[178:181], v172 offset:16384
	ds_read_b128 v[182:185], v172 offset:17408
	ds_read_b128 v[186:189], v172 offset:18432
	ds_read_b128 v[190:193], v172 offset:19456
	ds_read_b128 v[202:205], v172 offset:20480
	ds_read_b128 v[206:209], v172 offset:21504
	ds_read_b128 v[210:213], v172 offset:22528
	global_load_lds_dwordx4 v136, s[48:49]
	s_mov_b32 m0, s54
	ds_read_b128 v[214:217], v172 offset:23552
	global_load_lds_dwordx4 v140, s[48:49]
	s_barrier
	s_waitcnt lgkmcnt(0)
	v_mfma_f32_16x16x32_bf16 v[80:83], v[132:135], v[178:181], v[80:83]
	v_mfma_f32_16x16x32_bf16 v[76:79], v[168:171], v[178:181], v[76:79]
	v_mfma_f32_16x16x32_bf16 v[72:75], v[132:135], v[186:189], v[72:75]
	v_mfma_f32_16x16x32_bf16 v[68:71], v[168:171], v[186:189], v[68:71]
	v_mfma_f32_16x16x32_bf16 v[64:67], v[132:135], v[202:205], v[64:67]
	v_mfma_f32_16x16x32_bf16 v[60:63], v[168:171], v[202:205], v[60:63]
	v_mfma_f32_16x16x32_bf16 v[56:59], v[132:135], v[210:213], v[56:59]
	v_mfma_f32_16x16x32_bf16 v[52:55], v[168:171], v[210:213], v[52:55]
	v_mfma_f32_16x16x32_bf16 v[80:83], v[164:167], v[182:185], v[80:83]
	v_mfma_f32_16x16x32_bf16 v[76:79], v[174:177], v[182:185], v[76:79]
	v_mfma_f32_16x16x32_bf16 v[72:75], v[164:167], v[190:193], v[72:75]
	v_mfma_f32_16x16x32_bf16 v[68:71], v[174:177], v[190:193], v[68:71]
	v_mfma_f32_16x16x32_bf16 v[64:67], v[164:167], v[206:209], v[64:67]
	v_mfma_f32_16x16x32_bf16 v[60:63], v[174:177], v[206:209], v[60:63]
	v_mfma_f32_16x16x32_bf16 v[56:59], v[164:167], v[214:217], v[56:59]
	v_mfma_f32_16x16x32_bf16 v[52:55], v[174:177], v[214:217], v[52:55]
	s_barrier
	s_add_i32 s27, s27, s52
	s_mov_b32 m0, s27
	s_add_u32 s30, s46, 0xc0000
	s_addc_u32 s31, s47, 0
	global_load_lds_dwordx4 v138, s[30:31]
	s_add_i32 m0, s27, 0x2000
	s_waitcnt vmcnt(5)
	global_load_lds_dwordx4 v142, s[30:31]
	s_barrier
	v_mfma_f32_16x16x32_bf16 v[48:51], v[236:239], v[178:181], v[48:51]
	v_mfma_f32_16x16x32_bf16 v[44:47], v[244:247], v[178:181], v[44:47]
	v_mfma_f32_16x16x32_bf16 v[40:43], v[236:239], v[186:189], v[40:43]
	v_mfma_f32_16x16x32_bf16 v[36:39], v[244:247], v[186:189], v[36:39]
	v_mfma_f32_16x16x32_bf16 v[32:35], v[236:239], v[202:205], v[32:35]
	v_mfma_f32_16x16x32_bf16 v[28:31], v[244:247], v[202:205], v[28:31]
	v_mfma_f32_16x16x32_bf16 v[24:27], v[236:239], v[210:213], v[24:27]
	v_mfma_f32_16x16x32_bf16 v[20:23], v[244:247], v[210:213], v[20:23]
	v_mfma_f32_16x16x32_bf16 v[48:51], v[240:243], v[182:185], v[48:51]
	v_mfma_f32_16x16x32_bf16 v[44:47], v[248:251], v[182:185], v[44:47]
	v_mfma_f32_16x16x32_bf16 v[40:43], v[240:243], v[190:193], v[40:43]
	v_mfma_f32_16x16x32_bf16 v[36:39], v[248:251], v[190:193], v[36:39]
	v_mfma_f32_16x16x32_bf16 v[32:35], v[240:243], v[206:209], v[32:35]
	v_mfma_f32_16x16x32_bf16 v[28:31], v[248:251], v[206:209], v[28:31]
	v_mfma_f32_16x16x32_bf16 v[24:27], v[240:243], v[214:217], v[24:27]
	v_mfma_f32_16x16x32_bf16 v[20:23], v[248:251], v[214:217], v[20:23]
	s_add_i32 s27, 0, 0x18000
	s_barrier
	ds_read_b128 v[132:135], v1 offset:32768
	ds_read_b128 v[164:167], v1 offset:33792
	ds_read_b128 v[168:171], v1 offset:34816
	ds_read_b128 v[174:177], v1 offset:35840
	s_add_u32 s30, s48, 0x1a0000
	s_addc_u32 s31, s49, 0
	s_mov_b32 m0, s55
	ds_read_b128 v[178:181], v172 offset:32768
	ds_read_b128 v[182:185], v172 offset:33792
	ds_read_b128 v[186:189], v172 offset:34816
	ds_read_b128 v[190:193], v172 offset:35840
	ds_read_b128 v[202:205], v172 offset:36864
	ds_read_b128 v[206:209], v172 offset:37888
	ds_read_b128 v[210:213], v172 offset:38912
	global_load_lds_dwordx4 v136, s[30:31]
	s_mov_b32 m0, s56
	ds_read_b128 v[214:217], v172 offset:39936
	global_load_lds_dwordx4 v140, s[30:31]
	s_waitcnt lgkmcnt(8)
	s_barrier
	s_waitcnt lgkmcnt(0)
	v_mfma_f32_16x16x32_bf16 v[4:7], v[132:135], v[178:181], v[4:7]
	v_mfma_f32_16x16x32_bf16 v[8:11], v[168:171], v[178:181], v[8:11]
	v_mfma_f32_16x16x32_bf16 v[128:131], v[132:135], v[186:189], v[128:131]
	v_mfma_f32_16x16x32_bf16 v[124:127], v[168:171], v[186:189], v[124:127]
	v_mfma_f32_16x16x32_bf16 v[120:123], v[132:135], v[202:205], v[120:123]
	v_mfma_f32_16x16x32_bf16 v[116:119], v[168:171], v[202:205], v[116:119]
	v_mfma_f32_16x16x32_bf16 v[112:115], v[132:135], v[210:213], v[112:115]
	v_mfma_f32_16x16x32_bf16 v[108:111], v[168:171], v[210:213], v[108:111]
	v_mfma_f32_16x16x32_bf16 v[4:7], v[164:167], v[182:185], v[4:7]
	v_mfma_f32_16x16x32_bf16 v[8:11], v[174:177], v[182:185], v[8:11]
	v_mfma_f32_16x16x32_bf16 v[128:131], v[164:167], v[190:193], v[128:131]
	v_mfma_f32_16x16x32_bf16 v[124:127], v[174:177], v[190:193], v[124:127]
	v_mfma_f32_16x16x32_bf16 v[120:123], v[164:167], v[206:209], v[120:123]
	v_mfma_f32_16x16x32_bf16 v[116:119], v[174:177], v[206:209], v[116:119]
	v_mfma_f32_16x16x32_bf16 v[112:115], v[164:167], v[214:217], v[112:115]
	v_mfma_f32_16x16x32_bf16 v[108:111], v[174:177], v[214:217], v[108:111]
	s_barrier
	s_add_i32 s36, 0, 0x1c000
	s_add_i32 s27, s27, s52
	s_mov_b32 m0, s27
	ds_read_b128 v[236:239], v1 offset:49152
	ds_read_b128 v[240:243], v1 offset:50176
	ds_read_b128 v[244:247], v1 offset:51200
	s_add_u32 s98, s46, 0x80
	s_addc_u32 s99, s47, 0
	global_load_lds_dwordx4 v138, s[98:99]
	s_add_i32 m0, s27, 0x2000
	ds_read_b128 v[248:251], v1 offset:52224
	global_load_lds_dwordx4 v142, s[98:99]
	s_barrier
	s_waitcnt lgkmcnt(0)
	v_mfma_f32_16x16x32_bf16 v[12:15], v[236:239], v[178:181], v[12:15]
	v_mfma_f32_16x16x32_bf16 v[16:19], v[244:247], v[178:181], v[16:19]
	v_mfma_f32_16x16x32_bf16 v[104:107], v[236:239], v[186:189], v[104:107]
	v_mfma_f32_16x16x32_bf16 v[100:103], v[244:247], v[186:189], v[100:103]
	v_mfma_f32_16x16x32_bf16 v[96:99], v[236:239], v[202:205], v[96:99]
	v_mfma_f32_16x16x32_bf16 v[92:95], v[244:247], v[202:205], v[92:95]
	v_mfma_f32_16x16x32_bf16 v[88:91], v[236:239], v[210:213], v[88:91]
	v_mfma_f32_16x16x32_bf16 v[84:87], v[244:247], v[210:213], v[84:87]
	v_mfma_f32_16x16x32_bf16 v[12:15], v[240:243], v[182:185], v[12:15]
	v_mfma_f32_16x16x32_bf16 v[16:19], v[248:251], v[182:185], v[16:19]
	v_mfma_f32_16x16x32_bf16 v[104:107], v[240:243], v[190:193], v[104:107]
	v_mfma_f32_16x16x32_bf16 v[100:103], v[248:251], v[190:193], v[100:103]
	v_mfma_f32_16x16x32_bf16 v[96:99], v[240:243], v[206:209], v[96:99]
	v_mfma_f32_16x16x32_bf16 v[92:95], v[248:251], v[206:209], v[92:95]
	v_mfma_f32_16x16x32_bf16 v[88:91], v[240:243], v[214:217], v[88:91]
	v_mfma_f32_16x16x32_bf16 v[84:87], v[248:251], v[214:217], v[84:87]
	s_mov_b32 m0, s59
	s_barrier
	ds_read_b128 v[178:181], v172 offset:49152
	ds_read_b128 v[182:185], v172 offset:50176
	ds_read_b128 v[186:189], v172 offset:51200
	ds_read_b128 v[190:193], v172 offset:52224
	ds_read_b128 v[202:205], v172 offset:53248
	ds_read_b128 v[206:209], v172 offset:54272
	ds_read_b128 v[210:213], v172 offset:55296
	s_add_u32 s98, s48, 0x80
	s_addc_u32 s99, s49, 0
	global_load_lds_dwordx4 v136, s[98:99]
	s_mov_b32 m0, s60
	ds_read_b128 v[214:217], v172 offset:56320
	global_load_lds_dwordx4 v140, s[98:99]
	s_barrier
	s_waitcnt lgkmcnt(0)
	v_mfma_f32_16x16x32_bf16 v[80:83], v[132:135], v[178:181], v[80:83]
	v_mfma_f32_16x16x32_bf16 v[76:79], v[168:171], v[178:181], v[76:79]
	v_mfma_f32_16x16x32_bf16 v[72:75], v[132:135], v[186:189], v[72:75]
	v_mfma_f32_16x16x32_bf16 v[68:71], v[168:171], v[186:189], v[68:71]
	v_mfma_f32_16x16x32_bf16 v[64:67], v[132:135], v[202:205], v[64:67]
	v_mfma_f32_16x16x32_bf16 v[60:63], v[168:171], v[202:205], v[60:63]
	v_mfma_f32_16x16x32_bf16 v[56:59], v[132:135], v[210:213], v[56:59]
	v_mfma_f32_16x16x32_bf16 v[52:55], v[168:171], v[210:213], v[52:55]
	v_mfma_f32_16x16x32_bf16 v[80:83], v[164:167], v[182:185], v[80:83]
	v_mfma_f32_16x16x32_bf16 v[76:79], v[174:177], v[182:185], v[76:79]
	v_mfma_f32_16x16x32_bf16 v[72:75], v[164:167], v[190:193], v[72:75]
	v_mfma_f32_16x16x32_bf16 v[68:71], v[174:177], v[190:193], v[68:71]
	v_mfma_f32_16x16x32_bf16 v[64:67], v[164:167], v[206:209], v[64:67]
	v_mfma_f32_16x16x32_bf16 v[60:63], v[174:177], v[206:209], v[60:63]
	v_mfma_f32_16x16x32_bf16 v[56:59], v[164:167], v[214:217], v[56:59]
	v_mfma_f32_16x16x32_bf16 v[52:55], v[174:177], v[214:217], v[52:55]
	s_barrier
	s_add_i32 s27, s36, s52
	s_mov_b32 m0, s27
	s_add_u32 s30, s46, 0xc0080
	s_addc_u32 s31, s47, 0
	global_load_lds_dwordx4 v138, s[30:31]
	s_add_i32 m0, s27, 0x2000
	s_waitcnt vmcnt(5)
	global_load_lds_dwordx4 v142, s[30:31]
	s_barrier
	v_mfma_f32_16x16x32_bf16 v[48:51], v[236:239], v[178:181], v[48:51]
	v_mfma_f32_16x16x32_bf16 v[44:47], v[244:247], v[178:181], v[44:47]
	v_mfma_f32_16x16x32_bf16 v[40:43], v[236:239], v[186:189], v[40:43]
	v_mfma_f32_16x16x32_bf16 v[36:39], v[244:247], v[186:189], v[36:39]
	v_mfma_f32_16x16x32_bf16 v[32:35], v[236:239], v[202:205], v[32:35]
	v_mfma_f32_16x16x32_bf16 v[28:31], v[244:247], v[202:205], v[28:31]
	v_mfma_f32_16x16x32_bf16 v[24:27], v[236:239], v[210:213], v[24:27]
	v_mfma_f32_16x16x32_bf16 v[20:23], v[244:247], v[210:213], v[20:23]
	v_mfma_f32_16x16x32_bf16 v[48:51], v[240:243], v[182:185], v[48:51]
	v_mfma_f32_16x16x32_bf16 v[44:47], v[248:251], v[182:185], v[44:47]
	v_mfma_f32_16x16x32_bf16 v[40:43], v[240:243], v[190:193], v[40:43]
	v_mfma_f32_16x16x32_bf16 v[36:39], v[248:251], v[190:193], v[36:39]
	v_mfma_f32_16x16x32_bf16 v[32:35], v[240:243], v[206:209], v[32:35]
	v_mfma_f32_16x16x32_bf16 v[28:31], v[248:251], v[206:209], v[28:31]
	v_mfma_f32_16x16x32_bf16 v[24:27], v[240:243], v[214:217], v[24:27]
	v_mfma_f32_16x16x32_bf16 v[20:23], v[248:251], v[214:217], v[20:23]
	s_add_u32 s24, s24, 0x100
	s_addc_u32 s25, s25, 0
	s_cmp_ge_i32 s26, s22
	s_mov_b64 s[40:41], s[44:45]
	s_mov_b32 s27, s26
	s_barrier
	s_cbranch_scc0 .LBB0_175
	s_cmpk_gt_u32 s51, 0xff
	s_cbranch_scc1 .Lep_a_175
	s_barrier
.Lep_a_175:
	s_lshl_b32 s46, s66, 8
	v_lshl_or_b32 v0, s20, 8, v159
	s_mov_b32 s44, 0xbfb8aa3b
	s_mov_b32 s45, 0xbfb8aa3b
	v_lshlrev_b32_e32 v0, 1, v0
	v_add_u32_e32 v0, 0x1000, v0
	s_cmp_lg_u32 s21, 1
	s_cbranch_scc0 .Lg2_kind1
	v_readlane_b32 s22, v252, 34
	v_readlane_b32 s23, v252, 35
	v_add_u32_e32 v2, s46, v144
	v_mad_u32_u24 v2, v2, s29, v0
	global_load_dwordx4 v[132:135], v2, s[96:97] offset:2048
	v_add_u32_e32 v2, s46, v144
	v_mad_u32_u24 v2, v2, s29, v0
	global_load_dwordx4 v[178:181], v2, s[96:97] offset:2304
	v_add_u32_e32 v2, s46, v146
	v_mad_u32_u24 v2, v2, s29, v0
	global_load_dwordx4 v[182:185], v2, s[96:97] offset:2048
	v_add_u32_e32 v2, s46, v146
	v_mad_u32_u24 v2, v2, s29, v0
	global_load_dwordx4 v[186:189], v2, s[96:97] offset:2304
	v_add_u32_e32 v2, s46, v148
	v_mad_u32_u24 v2, v2, s29, v0
	global_load_dwordx4 v[190:193], v2, s[96:97] offset:2048
	v_add_u32_e32 v2, s46, v148
	v_mad_u32_u24 v2, v2, s29, v0
	global_load_dwordx4 v[202:205], v2, s[96:97] offset:2304
	v_add_u32_e32 v2, s46, v150
	v_mad_u32_u24 v2, v2, s29, v0
	global_load_dwordx4 v[206:209], v2, s[96:97] offset:2048
	v_add_u32_e32 v2, s46, v150
	v_mad_u32_u24 v2, v2, s29, v0
	global_load_dwordx4 v[210:213], v2, s[96:97] offset:2304
	v_add_u32_e32 v2, s46, v152
	v_mad_u32_u24 v2, v2, s29, v0
	global_load_dwordx4 v[214:217], v2, s[96:97] offset:2048
	v_add_u32_e32 v2, s46, v152
	v_mad_u32_u24 v2, v2, s29, v0
	global_load_dwordx4 v[236:239], v2, s[96:97] offset:2304
	v_add_u32_e32 v2, s46, v154
	v_mad_u32_u24 v2, v2, s29, v0
	global_load_dwordx4 v[240:243], v2, s[96:97] offset:2048
	v_add_u32_e32 v2, s46, v154
	v_mad_u32_u24 v2, v2, s29, v0
	global_load_dwordx4 v[244:247], v2, s[96:97] offset:2304
	v_add_u32_e32 v2, s46, v156
	v_mad_u32_u24 v2, v2, s29, v0
	global_load_dwordx4 v[248:251], v2, s[96:97] offset:2048
	s_waitcnt vmcnt(12)
	v_lshlrev_b32_e32 v164, 16, v132
	v_and_b32_e32 v165, 0xffff0000, v132
	v_lshlrev_b32_e32 v166, 16, v133
	v_and_b32_e32 v167, 0xffff0000, v133
	v_lshlrev_b32_e32 v168, 16, v134
	v_and_b32_e32 v169, 0xffff0000, v134
	v_lshlrev_b32_e32 v170, 16, v135
	v_and_b32_e32 v171, 0xffff0000, v135
	v_add_u32_e32 v2, s46, v156
	v_mad_u32_u24 v2, v2, s29, v0
	global_load_dwordx4 v[132:135], v2, s[96:97] offset:2304
	v_add_u32_e32 v1, s46, v144
	v_lshl_add_u32 v1, v1, 11, v0
	v_med3_f32 v164, v164, s34, v227
	v_med3_f32 v165, v165, s34, v227
	v_med3_f32 v166, v166, s34, v227
	v_med3_f32 v167, v167, s34, v227
	v_med3_f32 v168, v168, s34, v227
	v_med3_f32 v169, v169, s34, v227
	v_med3_f32 v170, v170, s34, v227
	v_med3_f32 v171, v171, s34, v227
	v_pk_mul_f32 v[164:165], v[164:165], s[44:45]
	v_pk_mul_f32 v[166:167], v[166:167], s[44:45]
	v_pk_mul_f32 v[168:169], v[168:169], s[44:45]
	v_pk_mul_f32 v[170:171], v[170:171], s[44:45]
	v_exp_f32_e32 v164, v164
	v_exp_f32_e32 v165, v165
	v_exp_f32_e32 v166, v166
	v_exp_f32_e32 v167, v167
	v_exp_f32_e32 v168, v168
	v_exp_f32_e32 v169, v169
	v_exp_f32_e32 v170, v170
	v_exp_f32_e32 v171, v171
	v_pk_add_f32 v[164:165], v[164:165], 1.0 op_sel_hi:[1,0]
	v_pk_add_f32 v[166:167], v[166:167], 1.0 op_sel_hi:[1,0]
	v_pk_add_f32 v[168:169], v[168:169], 1.0 op_sel_hi:[1,0]
	v_pk_add_f32 v[170:171], v[170:171], 1.0 op_sel_hi:[1,0]
	v_rcp_f32_e32 v164, v164
	v_rcp_f32_e32 v165, v165
	v_rcp_f32_e32 v166, v166
	v_rcp_f32_e32 v167, v167
	v_rcp_f32_e32 v168, v168
	v_rcp_f32_e32 v169, v169
	v_rcp_f32_e32 v170, v170
	v_rcp_f32_e32 v171, v171
	v_pk_mul_f32 v[164:165], v[4:5], v[164:165]
	v_pk_mul_f32 v[166:167], v[6:7], v[166:167]
	v_pk_mul_f32 v[168:169], v[8:9], v[168:169]
	v_pk_mul_f32 v[170:171], v[10:11], v[170:171]
	v_cvt_pk_bf16_f32 v174, v164, v165
	v_cvt_pk_bf16_f32 v175, v166, v167
	v_cvt_pk_bf16_f32 v176, v168, v169
	v_cvt_pk_bf16_f32 v177, v170, v171
	global_store_dwordx4 v1, v[174:177], s[22:23] offset:-4096
	s_waitcnt vmcnt(13)
	v_lshlrev_b32_e32 v164, 16, v178
	v_and_b32_e32 v165, 0xffff0000, v178
	v_lshlrev_b32_e32 v166, 16, v179
	v_and_b32_e32 v167, 0xffff0000, v179
	v_lshlrev_b32_e32 v168, 16, v180
	v_and_b32_e32 v169, 0xffff0000, v180
	v_lshlrev_b32_e32 v170, 16, v181
	v_and_b32_e32 v171, 0xffff0000, v181
	v_add_u32_e32 v2, s46, v158
	v_mad_u32_u24 v2, v2, s29, v0
	global_load_dwordx4 v[178:181], v2, s[96:97] offset:2048
	v_med3_f32 v164, v164, s34, v227
	v_med3_f32 v165, v165, s34, v227
	v_med3_f32 v166, v166, s34, v227
	v_med3_f32 v167, v167, s34, v227
	v_med3_f32 v168, v168, s34, v227
	v_med3_f32 v169, v169, s34, v227
	v_med3_f32 v170, v170, s34, v227
	v_med3_f32 v171, v171, s34, v227
	v_pk_mul_f32 v[164:165], v[164:165], s[44:45]
	v_pk_mul_f32 v[166:167], v[166:167], s[44:45]
	v_pk_mul_f32 v[168:169], v[168:169], s[44:45]
	v_pk_mul_f32 v[170:171], v[170:171], s[44:45]
	v_exp_f32_e32 v164, v164
	v_exp_f32_e32 v165, v165
	v_exp_f32_e32 v166, v166
	v_exp_f32_e32 v167, v167
	v_exp_f32_e32 v168, v168
	v_exp_f32_e32 v169, v169
	v_exp_f32_e32 v170, v170
	v_exp_f32_e32 v171, v171
	v_pk_add_f32 v[164:165], v[164:165], 1.0 op_sel_hi:[1,0]
	v_pk_add_f32 v[166:167], v[166:167], 1.0 op_sel_hi:[1,0]
	v_pk_add_f32 v[168:169], v[168:169], 1.0 op_sel_hi:[1,0]
	v_pk_add_f32 v[170:171], v[170:171], 1.0 op_sel_hi:[1,0]
	v_rcp_f32_e32 v164, v164
	v_rcp_f32_e32 v165, v165
	v_rcp_f32_e32 v166, v166
	v_rcp_f32_e32 v167, v167
	v_rcp_f32_e32 v168, v168
	v_rcp_f32_e32 v169, v169
	v_rcp_f32_e32 v170, v170
	v_rcp_f32_e32 v171, v171
	v_pk_mul_f32 v[164:165], v[12:13], v[164:165]
	v_pk_mul_f32 v[166:167], v[14:15], v[166:167]
	v_pk_mul_f32 v[168:169], v[16:17], v[168:169]
	v_pk_mul_f32 v[170:171], v[18:19], v[170:171]
	v_cvt_pk_bf16_f32 v174, v164, v165
	v_cvt_pk_bf16_f32 v175, v166, v167
	v_cvt_pk_bf16_f32 v176, v168, v169
	v_cvt_pk_bf16_f32 v177, v170, v171
	global_store_dwordx4 v1, v[174:177], s[22:23] offset:-3840
	s_waitcnt vmcnt(14)
	v_lshlrev_b32_e32 v164, 16, v182
	v_and_b32_e32 v165, 0xffff0000, v182
	v_lshlrev_b32_e32 v166, 16, v183
	v_and_b32_e32 v167, 0xffff0000, v183
	v_lshlrev_b32_e32 v168, 16, v184
	v_and_b32_e32 v169, 0xffff0000, v184
	v_lshlrev_b32_e32 v170, 16, v185
	v_and_b32_e32 v171, 0xffff0000, v185
	v_add_u32_e32 v2, s46, v158
	v_mad_u32_u24 v2, v2, s29, v0
	global_load_dwordx4 v[182:185], v2, s[96:97] offset:2304
	v_add_u32_e32 v1, s46, v146
	v_lshl_add_u32 v1, v1, 11, v0
	v_med3_f32 v164, v164, s34, v227
	v_med3_f32 v165, v165, s34, v227
	v_med3_f32 v166, v166, s34, v227
	v_med3_f32 v167, v167, s34, v227
	v_med3_f32 v168, v168, s34, v227
	v_med3_f32 v169, v169, s34, v227
	v_med3_f32 v170, v170, s34, v227
	v_med3_f32 v171, v171, s34, v227
	v_pk_mul_f32 v[164:165], v[164:165], s[44:45]
	v_pk_mul_f32 v[166:167], v[166:167], s[44:45]
	v_pk_mul_f32 v[168:169], v[168:169], s[44:45]
	v_pk_mul_f32 v[170:171], v[170:171], s[44:45]
	v_exp_f32_e32 v164, v164
	v_exp_f32_e32 v165, v165
	v_exp_f32_e32 v166, v166
	v_exp_f32_e32 v167, v167
	v_exp_f32_e32 v168, v168
	v_exp_f32_e32 v169, v169
	v_exp_f32_e32 v170, v170
	v_exp_f32_e32 v171, v171
	v_pk_add_f32 v[164:165], v[164:165], 1.0 op_sel_hi:[1,0]
	v_pk_add_f32 v[166:167], v[166:167], 1.0 op_sel_hi:[1,0]
	v_pk_add_f32 v[168:169], v[168:169], 1.0 op_sel_hi:[1,0]
	v_pk_add_f32 v[170:171], v[170:171], 1.0 op_sel_hi:[1,0]
	v_rcp_f32_e32 v164, v164
	v_rcp_f32_e32 v165, v165
	v_rcp_f32_e32 v166, v166
	v_rcp_f32_e32 v167, v167
	v_rcp_f32_e32 v168, v168
	v_rcp_f32_e32 v169, v169
	v_rcp_f32_e32 v170, v170
	v_rcp_f32_e32 v171, v171
	v_pk_mul_f32 v[164:165], v[128:129], v[164:165]
	v_pk_mul_f32 v[166:167], v[130:131], v[166:167]
	v_pk_mul_f32 v[168:169], v[124:125], v[168:169]
	v_pk_mul_f32 v[170:171], v[126:127], v[170:171]
	v_cvt_pk_bf16_f32 v174, v164, v165
	v_cvt_pk_bf16_f32 v175, v166, v167
	v_cvt_pk_bf16_f32 v176, v168, v169
	v_cvt_pk_bf16_f32 v177, v170, v171
	global_store_dwordx4 v1, v[174:177], s[22:23] offset:-4096
	s_waitcnt vmcnt(15)
	v_lshlrev_b32_e32 v164, 16, v186
	v_and_b32_e32 v165, 0xffff0000, v186
	v_lshlrev_b32_e32 v166, 16, v187
	v_and_b32_e32 v167, 0xffff0000, v187
	v_lshlrev_b32_e32 v168, 16, v188
	v_and_b32_e32 v169, 0xffff0000, v188
	v_lshlrev_b32_e32 v170, 16, v189
	v_and_b32_e32 v171, 0xffff0000, v189
	v_med3_f32 v164, v164, s34, v227
	v_med3_f32 v165, v165, s34, v227
	v_med3_f32 v166, v166, s34, v227
	v_med3_f32 v167, v167, s34, v227
	v_med3_f32 v168, v168, s34, v227
	v_med3_f32 v169, v169, s34, v227
	v_med3_f32 v170, v170, s34, v227
	v_med3_f32 v171, v171, s34, v227
	v_pk_mul_f32 v[164:165], v[164:165], s[44:45]
	v_pk_mul_f32 v[166:167], v[166:167], s[44:45]
	v_pk_mul_f32 v[168:169], v[168:169], s[44:45]
	v_pk_mul_f32 v[170:171], v[170:171], s[44:45]
	v_exp_f32_e32 v164, v164
	v_exp_f32_e32 v165, v165
	v_exp_f32_e32 v166, v166
	v_exp_f32_e32 v167, v167
	v_exp_f32_e32 v168, v168
	v_exp_f32_e32 v169, v169
	v_exp_f32_e32 v170, v170
	v_exp_f32_e32 v171, v171
	v_pk_add_f32 v[164:165], v[164:165], 1.0 op_sel_hi:[1,0]
	v_pk_add_f32 v[166:167], v[166:167], 1.0 op_sel_hi:[1,0]
	v_pk_add_f32 v[168:169], v[168:169], 1.0 op_sel_hi:[1,0]
	v_pk_add_f32 v[170:171], v[170:171], 1.0 op_sel_hi:[1,0]
	v_rcp_f32_e32 v164, v164
	v_rcp_f32_e32 v165, v165
	v_rcp_f32_e32 v166, v166
	v_rcp_f32_e32 v167, v167
	v_rcp_f32_e32 v168, v168
	v_rcp_f32_e32 v169, v169
	v_rcp_f32_e32 v170, v170
	v_rcp_f32_e32 v171, v171
	v_pk_mul_f32 v[164:165], v[104:105], v[164:165]
	v_pk_mul_f32 v[166:167], v[106:107], v[166:167]
	v_pk_mul_f32 v[168:169], v[100:101], v[168:169]
	v_pk_mul_f32 v[170:171], v[102:103], v[170:171]
	v_cvt_pk_bf16_f32 v174, v164, v165
	v_cvt_pk_bf16_f32 v175, v166, v167
	v_cvt_pk_bf16_f32 v176, v168, v169
	v_cvt_pk_bf16_f32 v177, v170, v171
	global_store_dwordx4 v1, v[174:177], s[22:23] offset:-3840
	s_waitcnt vmcnt(15)
	v_lshlrev_b32_e32 v164, 16, v190
	v_and_b32_e32 v165, 0xffff0000, v190
	v_lshlrev_b32_e32 v166, 16, v191
	v_and_b32_e32 v167, 0xffff0000, v191
	v_lshlrev_b32_e32 v168, 16, v192
	v_and_b32_e32 v169, 0xffff0000, v192
	v_lshlrev_b32_e32 v170, 16, v193
	v_and_b32_e32 v171, 0xffff0000, v193
	v_add_u32_e32 v1, s46, v148
	v_lshl_add_u32 v1, v1, 11, v0
	v_med3_f32 v164, v164, s34, v227
	v_med3_f32 v165, v165, s34, v227
	v_med3_f32 v166, v166, s34, v227
	v_med3_f32 v167, v167, s34, v227
	v_med3_f32 v168, v168, s34, v227
	v_med3_f32 v169, v169, s34, v227
	v_med3_f32 v170, v170, s34, v227
	v_med3_f32 v171, v171, s34, v227
	v_pk_mul_f32 v[164:165], v[164:165], s[44:45]
	v_pk_mul_f32 v[166:167], v[166:167], s[44:45]
	v_pk_mul_f32 v[168:169], v[168:169], s[44:45]
	v_pk_mul_f32 v[170:171], v[170:171], s[44:45]
	v_exp_f32_e32 v164, v164
	v_exp_f32_e32 v165, v165
	v_exp_f32_e32 v166, v166
	v_exp_f32_e32 v167, v167
	v_exp_f32_e32 v168, v168
	v_exp_f32_e32 v169, v169
	v_exp_f32_e32 v170, v170
	v_exp_f32_e32 v171, v171
	v_pk_add_f32 v[164:165], v[164:165], 1.0 op_sel_hi:[1,0]
	v_pk_add_f32 v[166:167], v[166:167], 1.0 op_sel_hi:[1,0]
	v_pk_add_f32 v[168:169], v[168:169], 1.0 op_sel_hi:[1,0]
	v_pk_add_f32 v[170:171], v[170:171], 1.0 op_sel_hi:[1,0]
	v_rcp_f32_e32 v164, v164
	v_rcp_f32_e32 v165, v165
	v_rcp_f32_e32 v166, v166
	v_rcp_f32_e32 v167, v167
	v_rcp_f32_e32 v168, v168
	v_rcp_f32_e32 v169, v169
	v_rcp_f32_e32 v170, v170
	v_rcp_f32_e32 v171, v171
	v_pk_mul_f32 v[164:165], v[120:121], v[164:165]
	v_pk_mul_f32 v[166:167], v[122:123], v[166:167]
	v_pk_mul_f32 v[168:169], v[116:117], v[168:169]
	v_pk_mul_f32 v[170:171], v[118:119], v[170:171]
	v_cvt_pk_bf16_f32 v174, v164, v165
	v_cvt_pk_bf16_f32 v175, v166, v167
	v_cvt_pk_bf16_f32 v176, v168, v169
	v_cvt_pk_bf16_f32 v177, v170, v171
	global_store_dwordx4 v1, v[174:177], s[22:23] offset:-4096
	s_waitcnt vmcnt(15)
	v_lshlrev_b32_e32 v164, 16, v202
	v_and_b32_e32 v165, 0xffff0000, v202
	v_lshlrev_b32_e32 v166, 16, v203
	v_and_b32_e32 v167, 0xffff0000, v203
	v_lshlrev_b32_e32 v168, 16, v204
	v_and_b32_e32 v169, 0xffff0000, v204
	v_lshlrev_b32_e32 v170, 16, v205
	v_and_b32_e32 v171, 0xffff0000, v205
	v_med3_f32 v164, v164, s34, v227
	v_med3_f32 v165, v165, s34, v227
	v_med3_f32 v166, v166, s34, v227
	v_med3_f32 v167, v167, s34, v227
	v_med3_f32 v168, v168, s34, v227
	v_med3_f32 v169, v169, s34, v227
	v_med3_f32 v170, v170, s34, v227
	v_med3_f32 v171, v171, s34, v227
	v_pk_mul_f32 v[164:165], v[164:165], s[44:45]
	v_pk_mul_f32 v[166:167], v[166:167], s[44:45]
	v_pk_mul_f32 v[168:169], v[168:169], s[44:45]
	v_pk_mul_f32 v[170:171], v[170:171], s[44:45]
	v_exp_f32_e32 v164, v164
	v_exp_f32_e32 v165, v165
	v_exp_f32_e32 v166, v166
	v_exp_f32_e32 v167, v167
	v_exp_f32_e32 v168, v168
	v_exp_f32_e32 v169, v169
	v_exp_f32_e32 v170, v170
	v_exp_f32_e32 v171, v171
	v_pk_add_f32 v[164:165], v[164:165], 1.0 op_sel_hi:[1,0]
	v_pk_add_f32 v[166:167], v[166:167], 1.0 op_sel_hi:[1,0]
	v_pk_add_f32 v[168:169], v[168:169], 1.0 op_sel_hi:[1,0]
	v_pk_add_f32 v[170:171], v[170:171], 1.0 op_sel_hi:[1,0]
	v_rcp_f32_e32 v164, v164
	v_rcp_f32_e32 v165, v165
	v_rcp_f32_e32 v166, v166
	v_rcp_f32_e32 v167, v167
	v_rcp_f32_e32 v168, v168
	v_rcp_f32_e32 v169, v169
	v_rcp_f32_e32 v170, v170
	v_rcp_f32_e32 v171, v171
	v_pk_mul_f32 v[164:165], v[96:97], v[164:165]
	v_pk_mul_f32 v[166:167], v[98:99], v[166:167]
	v_pk_mul_f32 v[168:169], v[92:93], v[168:169]
	v_pk_mul_f32 v[170:171], v[94:95], v[170:171]
	v_cvt_pk_bf16_f32 v174, v164, v165
	v_cvt_pk_bf16_f32 v175, v166, v167
	v_cvt_pk_bf16_f32 v176, v168, v169
	v_cvt_pk_bf16_f32 v177, v170, v171
	global_store_dwordx4 v1, v[174:177], s[22:23] offset:-3840
	s_waitcnt vmcnt(15)
	v_lshlrev_b32_e32 v164, 16, v206
	v_and_b32_e32 v165, 0xffff0000, v206
	v_lshlrev_b32_e32 v166, 16, v207
	v_and_b32_e32 v167, 0xffff0000, v207
	v_lshlrev_b32_e32 v168, 16, v208
	v_and_b32_e32 v169, 0xffff0000, v208
	v_lshlrev_b32_e32 v170, 16, v209
	v_and_b32_e32 v171, 0xffff0000, v209
	v_add_u32_e32 v1, s46, v150
	v_lshl_add_u32 v1, v1, 11, v0
	v_med3_f32 v164, v164, s34, v227
	v_med3_f32 v165, v165, s34, v227
	v_med3_f32 v166, v166, s34, v227
	v_med3_f32 v167, v167, s34, v227
	v_med3_f32 v168, v168, s34, v227
	v_med3_f32 v169, v169, s34, v227
	v_med3_f32 v170, v170, s34, v227
	v_med3_f32 v171, v171, s34, v227
	v_pk_mul_f32 v[164:165], v[164:165], s[44:45]
	v_pk_mul_f32 v[166:167], v[166:167], s[44:45]
	v_pk_mul_f32 v[168:169], v[168:169], s[44:45]
	v_pk_mul_f32 v[170:171], v[170:171], s[44:45]
	v_exp_f32_e32 v164, v164
	v_exp_f32_e32 v165, v165
	v_exp_f32_e32 v166, v166
	v_exp_f32_e32 v167, v167
	v_exp_f32_e32 v168, v168
	v_exp_f32_e32 v169, v169
	v_exp_f32_e32 v170, v170
	v_exp_f32_e32 v171, v171
	v_pk_add_f32 v[164:165], v[164:165], 1.0 op_sel_hi:[1,0]
	v_pk_add_f32 v[166:167], v[166:167], 1.0 op_sel_hi:[1,0]
	v_pk_add_f32 v[168:169], v[168:169], 1.0 op_sel_hi:[1,0]
	v_pk_add_f32 v[170:171], v[170:171], 1.0 op_sel_hi:[1,0]
	v_rcp_f32_e32 v164, v164
	v_rcp_f32_e32 v165, v165
	v_rcp_f32_e32 v166, v166
	v_rcp_f32_e32 v167, v167
	v_rcp_f32_e32 v168, v168
	v_rcp_f32_e32 v169, v169
	v_rcp_f32_e32 v170, v170
	v_rcp_f32_e32 v171, v171
	v_pk_mul_f32 v[164:165], v[112:113], v[164:165]
	v_pk_mul_f32 v[166:167], v[114:115], v[166:167]
	v_pk_mul_f32 v[168:169], v[108:109], v[168:169]
	v_pk_mul_f32 v[170:171], v[110:111], v[170:171]
	v_cvt_pk_bf16_f32 v174, v164, v165
	v_cvt_pk_bf16_f32 v175, v166, v167
	v_cvt_pk_bf16_f32 v176, v168, v169
	v_cvt_pk_bf16_f32 v177, v170, v171
	global_store_dwordx4 v1, v[174:177], s[22:23] offset:-4096
	s_waitcnt vmcnt(15)
	v_lshlrev_b32_e32 v164, 16, v210
	v_and_b32_e32 v165, 0xffff0000, v210
	v_lshlrev_b32_e32 v166, 16, v211
	v_and_b32_e32 v167, 0xffff0000, v211
	v_lshlrev_b32_e32 v168, 16, v212
	v_and_b32_e32 v169, 0xffff0000, v212
	v_lshlrev_b32_e32 v170, 16, v213
	v_and_b32_e32 v171, 0xffff0000, v213
	v_med3_f32 v164, v164, s34, v227
	v_med3_f32 v165, v165, s34, v227
	v_med3_f32 v166, v166, s34, v227
	v_med3_f32 v167, v167, s34, v227
	v_med3_f32 v168, v168, s34, v227
	v_med3_f32 v169, v169, s34, v227
	v_med3_f32 v170, v170, s34, v227
	v_med3_f32 v171, v171, s34, v227
	v_pk_mul_f32 v[164:165], v[164:165], s[44:45]
	v_pk_mul_f32 v[166:167], v[166:167], s[44:45]
	v_pk_mul_f32 v[168:169], v[168:169], s[44:45]
	v_pk_mul_f32 v[170:171], v[170:171], s[44:45]
	v_exp_f32_e32 v164, v164
	v_exp_f32_e32 v165, v165
	v_exp_f32_e32 v166, v166
	v_exp_f32_e32 v167, v167
	v_exp_f32_e32 v168, v168
	v_exp_f32_e32 v169, v169
	v_exp_f32_e32 v170, v170
	v_exp_f32_e32 v171, v171
	v_pk_add_f32 v[164:165], v[164:165], 1.0 op_sel_hi:[1,0]
	v_pk_add_f32 v[166:167], v[166:167], 1.0 op_sel_hi:[1,0]
	v_pk_add_f32 v[168:169], v[168:169], 1.0 op_sel_hi:[1,0]
	v_pk_add_f32 v[170:171], v[170:171], 1.0 op_sel_hi:[1,0]
	v_rcp_f32_e32 v164, v164
	v_rcp_f32_e32 v165, v165
	v_rcp_f32_e32 v166, v166
	v_rcp_f32_e32 v167, v167
	v_rcp_f32_e32 v168, v168
	v_rcp_f32_e32 v169, v169
	v_rcp_f32_e32 v170, v170
	v_rcp_f32_e32 v171, v171
	v_pk_mul_f32 v[164:165], v[88:89], v[164:165]
	v_pk_mul_f32 v[166:167], v[90:91], v[166:167]
	v_pk_mul_f32 v[168:169], v[84:85], v[168:169]
	v_pk_mul_f32 v[170:171], v[86:87], v[170:171]
	v_cvt_pk_bf16_f32 v174, v164, v165
	v_cvt_pk_bf16_f32 v175, v166, v167
	v_cvt_pk_bf16_f32 v176, v168, v169
	v_cvt_pk_bf16_f32 v177, v170, v171
	global_store_dwordx4 v1, v[174:177], s[22:23] offset:-3840
	s_waitcnt vmcnt(15)
	v_lshlrev_b32_e32 v164, 16, v214
	v_and_b32_e32 v165, 0xffff0000, v214
	v_lshlrev_b32_e32 v166, 16, v215
	v_and_b32_e32 v167, 0xffff0000, v215
	v_lshlrev_b32_e32 v168, 16, v216
	v_and_b32_e32 v169, 0xffff0000, v216
	v_lshlrev_b32_e32 v170, 16, v217
	v_and_b32_e32 v171, 0xffff0000, v217
	v_add_u32_e32 v1, s46, v152
	v_lshl_add_u32 v1, v1, 11, v0
	v_med3_f32 v164, v164, s34, v227
	v_med3_f32 v165, v165, s34, v227
	v_med3_f32 v166, v166, s34, v227
	v_med3_f32 v167, v167, s34, v227
	v_med3_f32 v168, v168, s34, v227
	v_med3_f32 v169, v169, s34, v227
	v_med3_f32 v170, v170, s34, v227
	v_med3_f32 v171, v171, s34, v227
	v_pk_mul_f32 v[164:165], v[164:165], s[44:45]
	v_pk_mul_f32 v[166:167], v[166:167], s[44:45]
	v_pk_mul_f32 v[168:169], v[168:169], s[44:45]
	v_pk_mul_f32 v[170:171], v[170:171], s[44:45]
	v_exp_f32_e32 v164, v164
	v_exp_f32_e32 v165, v165
	v_exp_f32_e32 v166, v166
	v_exp_f32_e32 v167, v167
	v_exp_f32_e32 v168, v168
	v_exp_f32_e32 v169, v169
	v_exp_f32_e32 v170, v170
	v_exp_f32_e32 v171, v171
	v_pk_add_f32 v[164:165], v[164:165], 1.0 op_sel_hi:[1,0]
	v_pk_add_f32 v[166:167], v[166:167], 1.0 op_sel_hi:[1,0]
	v_pk_add_f32 v[168:169], v[168:169], 1.0 op_sel_hi:[1,0]
	v_pk_add_f32 v[170:171], v[170:171], 1.0 op_sel_hi:[1,0]
	v_rcp_f32_e32 v164, v164
	v_rcp_f32_e32 v165, v165
	v_rcp_f32_e32 v166, v166
	v_rcp_f32_e32 v167, v167
	v_rcp_f32_e32 v168, v168
	v_rcp_f32_e32 v169, v169
	v_rcp_f32_e32 v170, v170
	v_rcp_f32_e32 v171, v171
	v_pk_mul_f32 v[164:165], v[80:81], v[164:165]
	v_pk_mul_f32 v[166:167], v[82:83], v[166:167]
	v_pk_mul_f32 v[168:169], v[76:77], v[168:169]
	v_pk_mul_f32 v[170:171], v[78:79], v[170:171]
	v_cvt_pk_bf16_f32 v174, v164, v165
	v_cvt_pk_bf16_f32 v175, v166, v167
	v_cvt_pk_bf16_f32 v176, v168, v169
	v_cvt_pk_bf16_f32 v177, v170, v171
	global_store_dwordx4 v1, v[174:177], s[22:23] offset:-4096
	s_waitcnt vmcnt(15)
	v_lshlrev_b32_e32 v164, 16, v236
	v_and_b32_e32 v165, 0xffff0000, v236
	v_lshlrev_b32_e32 v166, 16, v237
	v_and_b32_e32 v167, 0xffff0000, v237
	v_lshlrev_b32_e32 v168, 16, v238
	v_and_b32_e32 v169, 0xffff0000, v238
	v_lshlrev_b32_e32 v170, 16, v239
	v_and_b32_e32 v171, 0xffff0000, v239
	v_med3_f32 v164, v164, s34, v227
	v_med3_f32 v165, v165, s34, v227
	v_med3_f32 v166, v166, s34, v227
	v_med3_f32 v167, v167, s34, v227
	v_med3_f32 v168, v168, s34, v227
	v_med3_f32 v169, v169, s34, v227
	v_med3_f32 v170, v170, s34, v227
	v_med3_f32 v171, v171, s34, v227
	v_pk_mul_f32 v[164:165], v[164:165], s[44:45]
	v_pk_mul_f32 v[166:167], v[166:167], s[44:45]
	v_pk_mul_f32 v[168:169], v[168:169], s[44:45]
	v_pk_mul_f32 v[170:171], v[170:171], s[44:45]
	v_exp_f32_e32 v164, v164
	v_exp_f32_e32 v165, v165
	v_exp_f32_e32 v166, v166
	v_exp_f32_e32 v167, v167
	v_exp_f32_e32 v168, v168
	v_exp_f32_e32 v169, v169
	v_exp_f32_e32 v170, v170
	v_exp_f32_e32 v171, v171
	v_pk_add_f32 v[164:165], v[164:165], 1.0 op_sel_hi:[1,0]
	v_pk_add_f32 v[166:167], v[166:167], 1.0 op_sel_hi:[1,0]
	v_pk_add_f32 v[168:169], v[168:169], 1.0 op_sel_hi:[1,0]
	v_pk_add_f32 v[170:171], v[170:171], 1.0 op_sel_hi:[1,0]
	v_rcp_f32_e32 v164, v164
	v_rcp_f32_e32 v165, v165
	v_rcp_f32_e32 v166, v166
	v_rcp_f32_e32 v167, v167
	v_rcp_f32_e32 v168, v168
	v_rcp_f32_e32 v169, v169
	v_rcp_f32_e32 v170, v170
	v_rcp_f32_e32 v171, v171
	v_pk_mul_f32 v[164:165], v[48:49], v[164:165]
	v_pk_mul_f32 v[166:167], v[50:51], v[166:167]
	v_pk_mul_f32 v[168:169], v[44:45], v[168:169]
	v_pk_mul_f32 v[170:171], v[46:47], v[170:171]
	v_cvt_pk_bf16_f32 v174, v164, v165
	v_cvt_pk_bf16_f32 v175, v166, v167
	v_cvt_pk_bf16_f32 v176, v168, v169
	v_cvt_pk_bf16_f32 v177, v170, v171
	global_store_dwordx4 v1, v[174:177], s[22:23] offset:-3840
	s_waitcnt vmcnt(15)
	v_lshlrev_b32_e32 v164, 16, v240
	v_and_b32_e32 v165, 0xffff0000, v240
	v_lshlrev_b32_e32 v166, 16, v241
	v_and_b32_e32 v167, 0xffff0000, v241
	v_lshlrev_b32_e32 v168, 16, v242
	v_and_b32_e32 v169, 0xffff0000, v242
	v_lshlrev_b32_e32 v170, 16, v243
	v_and_b32_e32 v171, 0xffff0000, v243
	v_add_u32_e32 v1, s46, v154
	v_lshl_add_u32 v1, v1, 11, v0
	v_med3_f32 v164, v164, s34, v227
	v_med3_f32 v165, v165, s34, v227
	v_med3_f32 v166, v166, s34, v227
	v_med3_f32 v167, v167, s34, v227
	v_med3_f32 v168, v168, s34, v227
	v_med3_f32 v169, v169, s34, v227
	v_med3_f32 v170, v170, s34, v227
	v_med3_f32 v171, v171, s34, v227
	v_pk_mul_f32 v[164:165], v[164:165], s[44:45]
	v_pk_mul_f32 v[166:167], v[166:167], s[44:45]
	v_pk_mul_f32 v[168:169], v[168:169], s[44:45]
	v_pk_mul_f32 v[170:171], v[170:171], s[44:45]
	v_exp_f32_e32 v164, v164
	v_exp_f32_e32 v165, v165
	v_exp_f32_e32 v166, v166
	v_exp_f32_e32 v167, v167
	v_exp_f32_e32 v168, v168
	v_exp_f32_e32 v169, v169
	v_exp_f32_e32 v170, v170
	v_exp_f32_e32 v171, v171
	v_pk_add_f32 v[164:165], v[164:165], 1.0 op_sel_hi:[1,0]
	v_pk_add_f32 v[166:167], v[166:167], 1.0 op_sel_hi:[1,0]
	v_pk_add_f32 v[168:169], v[168:169], 1.0 op_sel_hi:[1,0]
	v_pk_add_f32 v[170:171], v[170:171], 1.0 op_sel_hi:[1,0]
	v_rcp_f32_e32 v164, v164
	v_rcp_f32_e32 v165, v165
	v_rcp_f32_e32 v166, v166
	v_rcp_f32_e32 v167, v167
	v_rcp_f32_e32 v168, v168
	v_rcp_f32_e32 v169, v169
	v_rcp_f32_e32 v170, v170
	v_rcp_f32_e32 v171, v171
	v_pk_mul_f32 v[164:165], v[72:73], v[164:165]
	v_pk_mul_f32 v[166:167], v[74:75], v[166:167]
	v_pk_mul_f32 v[168:169], v[68:69], v[168:169]
	v_pk_mul_f32 v[170:171], v[70:71], v[170:171]
	v_cvt_pk_bf16_f32 v174, v164, v165
	v_cvt_pk_bf16_f32 v175, v166, v167
	v_cvt_pk_bf16_f32 v176, v168, v169
	v_cvt_pk_bf16_f32 v177, v170, v171
	global_store_dwordx4 v1, v[174:177], s[22:23] offset:-4096
	s_waitcnt vmcnt(15)
	v_lshlrev_b32_e32 v164, 16, v244
	v_and_b32_e32 v165, 0xffff0000, v244
	v_lshlrev_b32_e32 v166, 16, v245
	v_and_b32_e32 v167, 0xffff0000, v245
	v_lshlrev_b32_e32 v168, 16, v246
	v_and_b32_e32 v169, 0xffff0000, v246
	v_lshlrev_b32_e32 v170, 16, v247
	v_and_b32_e32 v171, 0xffff0000, v247
	v_med3_f32 v164, v164, s34, v227
	v_med3_f32 v165, v165, s34, v227
	v_med3_f32 v166, v166, s34, v227
	v_med3_f32 v167, v167, s34, v227
	v_med3_f32 v168, v168, s34, v227
	v_med3_f32 v169, v169, s34, v227
	v_med3_f32 v170, v170, s34, v227
	v_med3_f32 v171, v171, s34, v227
	v_pk_mul_f32 v[164:165], v[164:165], s[44:45]
	v_pk_mul_f32 v[166:167], v[166:167], s[44:45]
	v_pk_mul_f32 v[168:169], v[168:169], s[44:45]
	v_pk_mul_f32 v[170:171], v[170:171], s[44:45]
	v_exp_f32_e32 v164, v164
	v_exp_f32_e32 v165, v165
	v_exp_f32_e32 v166, v166
	v_exp_f32_e32 v167, v167
	v_exp_f32_e32 v168, v168
	v_exp_f32_e32 v169, v169
	v_exp_f32_e32 v170, v170
	v_exp_f32_e32 v171, v171
	v_pk_add_f32 v[164:165], v[164:165], 1.0 op_sel_hi:[1,0]
	v_pk_add_f32 v[166:167], v[166:167], 1.0 op_sel_hi:[1,0]
	v_pk_add_f32 v[168:169], v[168:169], 1.0 op_sel_hi:[1,0]
	v_pk_add_f32 v[170:171], v[170:171], 1.0 op_sel_hi:[1,0]
	v_rcp_f32_e32 v164, v164
	v_rcp_f32_e32 v165, v165
	v_rcp_f32_e32 v166, v166
	v_rcp_f32_e32 v167, v167
	v_rcp_f32_e32 v168, v168
	v_rcp_f32_e32 v169, v169
	v_rcp_f32_e32 v170, v170
	v_rcp_f32_e32 v171, v171
	v_pk_mul_f32 v[164:165], v[40:41], v[164:165]
	v_pk_mul_f32 v[166:167], v[42:43], v[166:167]
	v_pk_mul_f32 v[168:169], v[36:37], v[168:169]
	v_pk_mul_f32 v[170:171], v[38:39], v[170:171]
	v_cvt_pk_bf16_f32 v174, v164, v165
	v_cvt_pk_bf16_f32 v175, v166, v167
	v_cvt_pk_bf16_f32 v176, v168, v169
	v_cvt_pk_bf16_f32 v177, v170, v171
	global_store_dwordx4 v1, v[174:177], s[22:23] offset:-3840
	s_waitcnt vmcnt(15)
	v_lshlrev_b32_e32 v164, 16, v248
	v_and_b32_e32 v165, 0xffff0000, v248
	v_lshlrev_b32_e32 v166, 16, v249
	v_and_b32_e32 v167, 0xffff0000, v249
	v_lshlrev_b32_e32 v168, 16, v250
	v_and_b32_e32 v169, 0xffff0000, v250
	v_lshlrev_b32_e32 v170, 16, v251
	v_and_b32_e32 v171, 0xffff0000, v251
	v_add_u32_e32 v1, s46, v156
	v_lshl_add_u32 v1, v1, 11, v0
	v_med3_f32 v164, v164, s34, v227
	v_med3_f32 v165, v165, s34, v227
	v_med3_f32 v166, v166, s34, v227
	v_med3_f32 v167, v167, s34, v227
	v_med3_f32 v168, v168, s34, v227
	v_med3_f32 v169, v169, s34, v227
	v_med3_f32 v170, v170, s34, v227
	v_med3_f32 v171, v171, s34, v227
	v_pk_mul_f32 v[164:165], v[164:165], s[44:45]
	v_pk_mul_f32 v[166:167], v[166:167], s[44:45]
	v_pk_mul_f32 v[168:169], v[168:169], s[44:45]
	v_pk_mul_f32 v[170:171], v[170:171], s[44:45]
	v_exp_f32_e32 v164, v164
	v_exp_f32_e32 v165, v165
	v_exp_f32_e32 v166, v166
	v_exp_f32_e32 v167, v167
	v_exp_f32_e32 v168, v168
	v_exp_f32_e32 v169, v169
	v_exp_f32_e32 v170, v170
	v_exp_f32_e32 v171, v171
	v_pk_add_f32 v[164:165], v[164:165], 1.0 op_sel_hi:[1,0]
	v_pk_add_f32 v[166:167], v[166:167], 1.0 op_sel_hi:[1,0]
	v_pk_add_f32 v[168:169], v[168:169], 1.0 op_sel_hi:[1,0]
	v_pk_add_f32 v[170:171], v[170:171], 1.0 op_sel_hi:[1,0]
	v_rcp_f32_e32 v164, v164
	v_rcp_f32_e32 v165, v165
	v_rcp_f32_e32 v166, v166
	v_rcp_f32_e32 v167, v167
	v_rcp_f32_e32 v168, v168
	v_rcp_f32_e32 v169, v169
	v_rcp_f32_e32 v170, v170
	v_rcp_f32_e32 v171, v171
	v_pk_mul_f32 v[164:165], v[64:65], v[164:165]
	v_pk_mul_f32 v[166:167], v[66:67], v[166:167]
	v_pk_mul_f32 v[168:169], v[60:61], v[168:169]
	v_pk_mul_f32 v[170:171], v[62:63], v[170:171]
	v_cvt_pk_bf16_f32 v174, v164, v165
	v_cvt_pk_bf16_f32 v175, v166, v167
	v_cvt_pk_bf16_f32 v176, v168, v169
	v_cvt_pk_bf16_f32 v177, v170, v171
	global_store_dwordx4 v1, v[174:177], s[22:23] offset:-4096
	s_waitcnt vmcnt(15)
	v_lshlrev_b32_e32 v164, 16, v132
	v_and_b32_e32 v165, 0xffff0000, v132
	v_lshlrev_b32_e32 v166, 16, v133
	v_and_b32_e32 v167, 0xffff0000, v133
	v_lshlrev_b32_e32 v168, 16, v134
	v_and_b32_e32 v169, 0xffff0000, v134
	v_lshlrev_b32_e32 v170, 16, v135
	v_and_b32_e32 v171, 0xffff0000, v135
	v_med3_f32 v164, v164, s34, v227
	v_med3_f32 v165, v165, s34, v227
	v_med3_f32 v166, v166, s34, v227
	v_med3_f32 v167, v167, s34, v227
	v_med3_f32 v168, v168, s34, v227
	v_med3_f32 v169, v169, s34, v227
	v_med3_f32 v170, v170, s34, v227
	v_med3_f32 v171, v171, s34, v227
	v_pk_mul_f32 v[164:165], v[164:165], s[44:45]
	v_pk_mul_f32 v[166:167], v[166:167], s[44:45]
	v_pk_mul_f32 v[168:169], v[168:169], s[44:45]
	v_pk_mul_f32 v[170:171], v[170:171], s[44:45]
	v_exp_f32_e32 v164, v164
	v_exp_f32_e32 v165, v165
	v_exp_f32_e32 v166, v166
	v_exp_f32_e32 v167, v167
	v_exp_f32_e32 v168, v168
	v_exp_f32_e32 v169, v169
	v_exp_f32_e32 v170, v170
	v_exp_f32_e32 v171, v171
	v_pk_add_f32 v[164:165], v[164:165], 1.0 op_sel_hi:[1,0]
	v_pk_add_f32 v[166:167], v[166:167], 1.0 op_sel_hi:[1,0]
	v_pk_add_f32 v[168:169], v[168:169], 1.0 op_sel_hi:[1,0]
	v_pk_add_f32 v[170:171], v[170:171], 1.0 op_sel_hi:[1,0]
	v_rcp_f32_e32 v164, v164
	v_rcp_f32_e32 v165, v165
	v_rcp_f32_e32 v166, v166
	v_rcp_f32_e32 v167, v167
	v_rcp_f32_e32 v168, v168
	v_rcp_f32_e32 v169, v169
	v_rcp_f32_e32 v170, v170
	v_rcp_f32_e32 v171, v171
	v_pk_mul_f32 v[164:165], v[32:33], v[164:165]
	v_pk_mul_f32 v[166:167], v[34:35], v[166:167]
	v_pk_mul_f32 v[168:169], v[28:29], v[168:169]
	v_pk_mul_f32 v[170:171], v[30:31], v[170:171]
	v_cvt_pk_bf16_f32 v174, v164, v165
	v_cvt_pk_bf16_f32 v175, v166, v167
	v_cvt_pk_bf16_f32 v176, v168, v169
	v_cvt_pk_bf16_f32 v177, v170, v171
	global_store_dwordx4 v1, v[174:177], s[22:23] offset:-3840
	s_waitcnt vmcnt(14)
	v_lshlrev_b32_e32 v164, 16, v178
	v_and_b32_e32 v165, 0xffff0000, v178
	v_lshlrev_b32_e32 v166, 16, v179
	v_and_b32_e32 v167, 0xffff0000, v179
	v_lshlrev_b32_e32 v168, 16, v180
	v_and_b32_e32 v169, 0xffff0000, v180
	v_lshlrev_b32_e32 v170, 16, v181
	v_and_b32_e32 v171, 0xffff0000, v181
	v_add_u32_e32 v1, s46, v158
	v_lshl_add_u32 v1, v1, 11, v0
	v_med3_f32 v164, v164, s34, v227
	v_med3_f32 v165, v165, s34, v227
	v_med3_f32 v166, v166, s34, v227
	v_med3_f32 v167, v167, s34, v227
	v_med3_f32 v168, v168, s34, v227
	v_med3_f32 v169, v169, s34, v227
	v_med3_f32 v170, v170, s34, v227
	v_med3_f32 v171, v171, s34, v227
	v_pk_mul_f32 v[164:165], v[164:165], s[44:45]
	v_pk_mul_f32 v[166:167], v[166:167], s[44:45]
	v_pk_mul_f32 v[168:169], v[168:169], s[44:45]
	v_pk_mul_f32 v[170:171], v[170:171], s[44:45]
	v_exp_f32_e32 v164, v164
	v_exp_f32_e32 v165, v165
	v_exp_f32_e32 v166, v166
	v_exp_f32_e32 v167, v167
	v_exp_f32_e32 v168, v168
	v_exp_f32_e32 v169, v169
	v_exp_f32_e32 v170, v170
	v_exp_f32_e32 v171, v171
	v_pk_add_f32 v[164:165], v[164:165], 1.0 op_sel_hi:[1,0]
	v_pk_add_f32 v[166:167], v[166:167], 1.0 op_sel_hi:[1,0]
	v_pk_add_f32 v[168:169], v[168:169], 1.0 op_sel_hi:[1,0]
	v_pk_add_f32 v[170:171], v[170:171], 1.0 op_sel_hi:[1,0]
	v_rcp_f32_e32 v164, v164
	v_rcp_f32_e32 v165, v165
	v_rcp_f32_e32 v166, v166
	v_rcp_f32_e32 v167, v167
	v_rcp_f32_e32 v168, v168
	v_rcp_f32_e32 v169, v169
	v_rcp_f32_e32 v170, v170
	v_rcp_f32_e32 v171, v171
	v_pk_mul_f32 v[164:165], v[56:57], v[164:165]
	v_pk_mul_f32 v[166:167], v[58:59], v[166:167]
	v_pk_mul_f32 v[168:169], v[52:53], v[168:169]
	v_pk_mul_f32 v[170:171], v[54:55], v[170:171]
	v_cvt_pk_bf16_f32 v174, v164, v165
	v_cvt_pk_bf16_f32 v175, v166, v167
	v_cvt_pk_bf16_f32 v176, v168, v169
	v_cvt_pk_bf16_f32 v177, v170, v171
	global_store_dwordx4 v1, v[174:177], s[22:23] offset:-4096
	s_waitcnt vmcnt(13)
	v_lshlrev_b32_e32 v164, 16, v182
	v_and_b32_e32 v165, 0xffff0000, v182
	v_lshlrev_b32_e32 v166, 16, v183
	v_and_b32_e32 v167, 0xffff0000, v183
	v_lshlrev_b32_e32 v168, 16, v184
	v_and_b32_e32 v169, 0xffff0000, v184
	v_lshlrev_b32_e32 v170, 16, v185
	v_and_b32_e32 v171, 0xffff0000, v185
	v_med3_f32 v164, v164, s34, v227
	v_med3_f32 v165, v165, s34, v227
	v_med3_f32 v166, v166, s34, v227
	v_med3_f32 v167, v167, s34, v227
	v_med3_f32 v168, v168, s34, v227
	v_med3_f32 v169, v169, s34, v227
	v_med3_f32 v170, v170, s34, v227
	v_med3_f32 v171, v171, s34, v227
	v_pk_mul_f32 v[164:165], v[164:165], s[44:45]
	v_pk_mul_f32 v[166:167], v[166:167], s[44:45]
	v_pk_mul_f32 v[168:169], v[168:169], s[44:45]
	v_pk_mul_f32 v[170:171], v[170:171], s[44:45]
	v_exp_f32_e32 v164, v164
	v_exp_f32_e32 v165, v165
	v_exp_f32_e32 v166, v166
	v_exp_f32_e32 v167, v167
	v_exp_f32_e32 v168, v168
	v_exp_f32_e32 v169, v169
	v_exp_f32_e32 v170, v170
	v_exp_f32_e32 v171, v171
	v_pk_add_f32 v[164:165], v[164:165], 1.0 op_sel_hi:[1,0]
	v_pk_add_f32 v[166:167], v[166:167], 1.0 op_sel_hi:[1,0]
	v_pk_add_f32 v[168:169], v[168:169], 1.0 op_sel_hi:[1,0]
	v_pk_add_f32 v[170:171], v[170:171], 1.0 op_sel_hi:[1,0]
	v_rcp_f32_e32 v164, v164
	v_rcp_f32_e32 v165, v165
	v_rcp_f32_e32 v166, v166
	v_rcp_f32_e32 v167, v167
	v_rcp_f32_e32 v168, v168
	v_rcp_f32_e32 v169, v169
	v_rcp_f32_e32 v170, v170
	v_rcp_f32_e32 v171, v171
	v_pk_mul_f32 v[164:165], v[24:25], v[164:165]
	v_pk_mul_f32 v[166:167], v[26:27], v[166:167]
	v_pk_mul_f32 v[168:169], v[20:21], v[168:169]
	v_pk_mul_f32 v[170:171], v[22:23], v[170:171]
	v_cvt_pk_bf16_f32 v174, v164, v165
	v_cvt_pk_bf16_f32 v175, v166, v167
	v_cvt_pk_bf16_f32 v176, v168, v169
	v_cvt_pk_bf16_f32 v177, v170, v171
	global_store_dwordx4 v1, v[174:177], s[22:23] offset:-3840
	s_mov_b64 s[40:41], 0
	s_branch .LBB0_206

.LBB0_234:
	v_readlane_b32 s98, v255, 3
	v_readlane_b32 s99, v255, 4
	s_nop 0
	s_cmp_lg_u64 s[98:99], 0
	s_cbranch_scc1 .Lep_b_242
	s_barrier
.Lep_b_242:
	s_and_b64 vcc, exec, s[42:43]
	s_mov_b32 s66, s52
	s_mov_b32 s60, s54
	s_mov_b64 s[44:45], s[58:59]
	s_mov_b64 s[0:1], s[56:57]
	s_cbranch_vccnz .LBB0_314

.LBB0_242:
	s_add_u32 s23, s0, 0xfffc0080
	s_addc_u32 s24, s1, -1
	s_add_i32 s25, 0, 0x10000
	ds_read_b128 v[132:135], v216
	ds_read_b128 v[136:139], v216 offset:1024
	ds_read_b128 v[140:143], v216 offset:2048
	ds_read_b128 v[144:147], v216 offset:3072
	s_cmp_eq_u32 s22, 12
	s_cselect_b32 s47, s57, s24
	s_cselect_b32 s46, s56, s23
	s_cselect_b32 s45, s59, s21
	s_cselect_b32 s44, s58, s20
	s_add_i32 m0, s67, 0xc000
	ds_read_b128 v[148:151], v240
	ds_read_b128 v[152:155], v240 offset:1024
	ds_read_b128 v[156:159], v240 offset:2048
	ds_read_b128 v[160:163], v240 offset:3072
	ds_read_b128 v[164:167], v240 offset:4096
	ds_read_b128 v[168:171], v240 offset:5120
	ds_read_b128 v[172:175], v240 offset:6144
	global_load_lds_dwordx4 v194, s[0:1]
	s_add_i32 m0, s67, 0xe000
	ds_read_b128 v[204:207], v240 offset:7168
	global_load_lds_dwordx4 v202, s[0:1]
	s_waitcnt lgkmcnt(8)
	s_barrier
	s_waitcnt lgkmcnt(0)
	v_mfma_f32_16x16x32_bf16 v[128:131], v[132:135], v[148:151], v[128:131]
	v_mfma_f32_16x16x32_bf16 v[124:127], v[140:143], v[148:151], v[124:127]
	v_mfma_f32_16x16x32_bf16 v[120:123], v[132:135], v[156:159], v[120:123]
	v_mfma_f32_16x16x32_bf16 v[116:119], v[140:143], v[156:159], v[116:119]
	v_mfma_f32_16x16x32_bf16 v[112:115], v[132:135], v[164:167], v[112:115]
	v_mfma_f32_16x16x32_bf16 v[108:111], v[140:143], v[164:167], v[108:111]
	v_mfma_f32_16x16x32_bf16 v[104:107], v[132:135], v[172:175], v[104:107]
	v_mfma_f32_16x16x32_bf16 v[100:103], v[140:143], v[172:175], v[100:103]
	v_mfma_f32_16x16x32_bf16 v[128:131], v[136:139], v[152:155], v[128:131]
	v_mfma_f32_16x16x32_bf16 v[124:127], v[144:147], v[152:155], v[124:127]
	v_mfma_f32_16x16x32_bf16 v[120:123], v[136:139], v[160:163], v[120:123]
	v_mfma_f32_16x16x32_bf16 v[116:119], v[144:147], v[160:163], v[116:119]
	v_mfma_f32_16x16x32_bf16 v[112:115], v[136:139], v[168:171], v[112:115]
	v_mfma_f32_16x16x32_bf16 v[108:111], v[144:147], v[168:171], v[108:111]
	v_mfma_f32_16x16x32_bf16 v[104:107], v[136:139], v[204:207], v[104:107]
	v_mfma_f32_16x16x32_bf16 v[100:103], v[144:147], v[204:207], v[100:103]
	s_barrier
	s_add_i32 s23, 0, 0x14000
	s_add_i32 s24, s25, s61
	s_mov_b32 m0, s24
	ds_read_b128 v[208:211], v216 offset:16384
	ds_read_b128 v[212:215], v216 offset:17408
	ds_read_b128 v[242:245], v216 offset:18432
	global_load_lds_dwordx4 v176, s[44:45]
	s_add_i32 m0, s24, 0x2000
	ds_read_b128 v[246:249], v216 offset:19456
	global_load_lds_dwordx4 v180, s[44:45]
	s_barrier
	s_waitcnt lgkmcnt(0)
	v_mfma_f32_16x16x32_bf16 v[64:67], v[208:211], v[148:151], v[64:67]
	v_mfma_f32_16x16x32_bf16 v[60:63], v[242:245], v[148:151], v[60:63]
	v_mfma_f32_16x16x32_bf16 v[56:59], v[208:211], v[156:159], v[56:59]
	v_mfma_f32_16x16x32_bf16 v[52:55], v[242:245], v[156:159], v[52:55]
	v_mfma_f32_16x16x32_bf16 v[48:51], v[208:211], v[164:167], v[48:51]
	v_mfma_f32_16x16x32_bf16 v[44:47], v[242:245], v[164:167], v[44:47]
	v_mfma_f32_16x16x32_bf16 v[40:43], v[208:211], v[172:175], v[40:43]
	v_mfma_f32_16x16x32_bf16 v[36:39], v[242:245], v[172:175], v[36:39]
	v_mfma_f32_16x16x32_bf16 v[64:67], v[212:215], v[152:155], v[64:67]
	v_mfma_f32_16x16x32_bf16 v[60:63], v[246:249], v[152:155], v[60:63]
	v_mfma_f32_16x16x32_bf16 v[56:59], v[212:215], v[160:163], v[56:59]
	v_mfma_f32_16x16x32_bf16 v[52:55], v[246:249], v[160:163], v[52:55]
	v_mfma_f32_16x16x32_bf16 v[48:51], v[212:215], v[168:171], v[48:51]
	v_mfma_f32_16x16x32_bf16 v[44:47], v[246:249], v[168:171], v[44:47]
	v_mfma_f32_16x16x32_bf16 v[40:43], v[212:215], v[204:207], v[40:43]
	v_mfma_f32_16x16x32_bf16 v[36:39], v[246:249], v[204:207], v[36:39]
	s_mov_b32 m0, s67
	s_barrier
	ds_read_b128 v[148:151], v240 offset:16384
	ds_read_b128 v[152:155], v240 offset:17408
	ds_read_b128 v[156:159], v240 offset:18432
	ds_read_b128 v[160:163], v240 offset:19456
	ds_read_b128 v[164:167], v240 offset:20480
	ds_read_b128 v[168:171], v240 offset:21504
	ds_read_b128 v[172:175], v240 offset:22528
	global_load_lds_dwordx4 v0, s[46:47]
	s_mov_b32 m0, s74
	ds_read_b128 v[204:207], v240 offset:23552
	global_load_lds_dwordx4 v178, s[46:47]
	s_barrier
	s_waitcnt lgkmcnt(0)
	v_mfma_f32_16x16x32_bf16 v[96:99], v[132:135], v[148:151], v[96:99]
	v_mfma_f32_16x16x32_bf16 v[92:95], v[140:143], v[148:151], v[92:95]
	v_mfma_f32_16x16x32_bf16 v[88:91], v[132:135], v[156:159], v[88:91]
	v_mfma_f32_16x16x32_bf16 v[84:87], v[140:143], v[156:159], v[84:87]
	v_mfma_f32_16x16x32_bf16 v[80:83], v[132:135], v[164:167], v[80:83]
	v_mfma_f32_16x16x32_bf16 v[76:79], v[140:143], v[164:167], v[76:79]
	v_mfma_f32_16x16x32_bf16 v[72:75], v[132:135], v[172:175], v[72:75]
	v_mfma_f32_16x16x32_bf16 v[68:71], v[140:143], v[172:175], v[68:71]
	v_mfma_f32_16x16x32_bf16 v[96:99], v[136:139], v[152:155], v[96:99]
	v_mfma_f32_16x16x32_bf16 v[92:95], v[144:147], v[152:155], v[92:95]
	v_mfma_f32_16x16x32_bf16 v[88:91], v[136:139], v[160:163], v[88:91]
	v_mfma_f32_16x16x32_bf16 v[84:87], v[144:147], v[160:163], v[84:87]
	v_mfma_f32_16x16x32_bf16 v[80:83], v[136:139], v[168:171], v[80:83]
	v_mfma_f32_16x16x32_bf16 v[76:79], v[144:147], v[168:171], v[76:79]
	v_mfma_f32_16x16x32_bf16 v[72:75], v[136:139], v[204:207], v[72:75]
	v_mfma_f32_16x16x32_bf16 v[68:71], v[144:147], v[204:207], v[68:71]
	s_barrier
	s_add_i32 s23, s23, s61
	s_mov_b32 m0, s23
	s_add_u32 s24, s44, 0x40000
	s_addc_u32 s25, s45, 0
	global_load_lds_dwordx4 v176, s[24:25]
	s_add_i32 m0, s23, 0x2000
	s_waitcnt vmcnt(5)
	global_load_lds_dwordx4 v180, s[24:25]
	s_barrier
	v_mfma_f32_16x16x32_bf16 v[32:35], v[208:211], v[148:151], v[32:35]
	v_mfma_f32_16x16x32_bf16 v[28:31], v[242:245], v[148:151], v[28:31]
	v_mfma_f32_16x16x32_bf16 v[24:27], v[208:211], v[156:159], v[24:27]
	v_mfma_f32_16x16x32_bf16 v[20:23], v[242:245], v[156:159], v[20:23]
	v_mfma_f32_16x16x32_bf16 v[16:19], v[208:211], v[164:167], v[16:19]
	v_mfma_f32_16x16x32_bf16 v[12:15], v[242:245], v[164:167], v[12:15]
	v_mfma_f32_16x16x32_bf16 v[8:11], v[208:211], v[172:175], v[8:11]
	v_mfma_f32_16x16x32_bf16 v[4:7], v[242:245], v[172:175], v[4:7]
	v_mfma_f32_16x16x32_bf16 v[32:35], v[212:215], v[152:155], v[32:35]
	v_mfma_f32_16x16x32_bf16 v[28:31], v[246:249], v[152:155], v[28:31]
	v_mfma_f32_16x16x32_bf16 v[24:27], v[212:215], v[160:163], v[24:27]
	v_mfma_f32_16x16x32_bf16 v[20:23], v[246:249], v[160:163], v[20:23]
	v_mfma_f32_16x16x32_bf16 v[16:19], v[212:215], v[168:171], v[16:19]
	v_mfma_f32_16x16x32_bf16 v[12:15], v[246:249], v[168:171], v[12:15]
	v_mfma_f32_16x16x32_bf16 v[8:11], v[212:215], v[204:207], v[8:11]
	v_mfma_f32_16x16x32_bf16 v[4:7], v[246:249], v[204:207], v[4:7]
	s_add_i32 s23, 0, 0x18000
	s_barrier
	ds_read_b128 v[132:135], v216 offset:32768
	ds_read_b128 v[136:139], v216 offset:33792
	ds_read_b128 v[140:143], v216 offset:34816
	ds_read_b128 v[144:147], v216 offset:35840
	s_add_u32 s24, s46, 0x40000
	s_addc_u32 s25, s47, 0
	s_mov_b32 m0, s75
	ds_read_b128 v[148:151], v240 offset:32768
	ds_read_b128 v[152:155], v240 offset:33792
	ds_read_b128 v[156:159], v240 offset:34816
	ds_read_b128 v[160:163], v240 offset:35840
	ds_read_b128 v[164:167], v240 offset:36864
	ds_read_b128 v[168:171], v240 offset:37888
	ds_read_b128 v[172:175], v240 offset:38912
	global_load_lds_dwordx4 v0, s[24:25]
	s_mov_b32 m0, s82
	ds_read_b128 v[204:207], v240 offset:39936
	global_load_lds_dwordx4 v178, s[24:25]
	s_waitcnt lgkmcnt(8)
	s_barrier
	s_waitcnt lgkmcnt(0)
	v_mfma_f32_16x16x32_bf16 v[128:131], v[132:135], v[148:151], v[128:131]
	v_mfma_f32_16x16x32_bf16 v[124:127], v[140:143], v[148:151], v[124:127]
	v_mfma_f32_16x16x32_bf16 v[120:123], v[132:135], v[156:159], v[120:123]
	v_mfma_f32_16x16x32_bf16 v[116:119], v[140:143], v[156:159], v[116:119]
	v_mfma_f32_16x16x32_bf16 v[112:115], v[132:135], v[164:167], v[112:115]
	v_mfma_f32_16x16x32_bf16 v[108:111], v[140:143], v[164:167], v[108:111]
	v_mfma_f32_16x16x32_bf16 v[104:107], v[132:135], v[172:175], v[104:107]
	v_mfma_f32_16x16x32_bf16 v[100:103], v[140:143], v[172:175], v[100:103]
	v_mfma_f32_16x16x32_bf16 v[128:131], v[136:139], v[152:155], v[128:131]
	v_mfma_f32_16x16x32_bf16 v[124:127], v[144:147], v[152:155], v[124:127]
	v_mfma_f32_16x16x32_bf16 v[120:123], v[136:139], v[160:163], v[120:123]
	v_mfma_f32_16x16x32_bf16 v[116:119], v[144:147], v[160:163], v[116:119]
	v_mfma_f32_16x16x32_bf16 v[112:115], v[136:139], v[168:171], v[112:115]
	v_mfma_f32_16x16x32_bf16 v[108:111], v[144:147], v[168:171], v[108:111]
	v_mfma_f32_16x16x32_bf16 v[104:107], v[136:139], v[204:207], v[104:107]
	v_mfma_f32_16x16x32_bf16 v[100:103], v[144:147], v[204:207], v[100:103]
	s_barrier
	s_add_i32 s26, 0, 0x1c000
	s_add_i32 s23, s23, s61
	s_mov_b32 m0, s23
	ds_read_b128 v[208:211], v216 offset:49152
	ds_read_b128 v[212:215], v216 offset:50176
	ds_read_b128 v[242:245], v216 offset:51200
	s_add_u32 s98, s44, 0x80
	s_addc_u32 s99, s45, 0
	global_load_lds_dwordx4 v176, s[98:99]
	s_add_i32 m0, s23, 0x2000
	ds_read_b128 v[246:249], v216 offset:52224
	global_load_lds_dwordx4 v180, s[98:99]
	s_barrier
	s_waitcnt lgkmcnt(0)
	v_mfma_f32_16x16x32_bf16 v[64:67], v[208:211], v[148:151], v[64:67]
	v_mfma_f32_16x16x32_bf16 v[60:63], v[242:245], v[148:151], v[60:63]
	v_mfma_f32_16x16x32_bf16 v[56:59], v[208:211], v[156:159], v[56:59]
	v_mfma_f32_16x16x32_bf16 v[52:55], v[242:245], v[156:159], v[52:55]
	v_mfma_f32_16x16x32_bf16 v[48:51], v[208:211], v[164:167], v[48:51]
	v_mfma_f32_16x16x32_bf16 v[44:47], v[242:245], v[164:167], v[44:47]
	v_mfma_f32_16x16x32_bf16 v[40:43], v[208:211], v[172:175], v[40:43]
	v_mfma_f32_16x16x32_bf16 v[36:39], v[242:245], v[172:175], v[36:39]
	v_mfma_f32_16x16x32_bf16 v[64:67], v[212:215], v[152:155], v[64:67]
	v_mfma_f32_16x16x32_bf16 v[60:63], v[246:249], v[152:155], v[60:63]
	v_mfma_f32_16x16x32_bf16 v[56:59], v[212:215], v[160:163], v[56:59]
	v_mfma_f32_16x16x32_bf16 v[52:55], v[246:249], v[160:163], v[52:55]
	v_mfma_f32_16x16x32_bf16 v[48:51], v[212:215], v[168:171], v[48:51]
	v_mfma_f32_16x16x32_bf16 v[44:47], v[246:249], v[168:171], v[44:47]
	v_mfma_f32_16x16x32_bf16 v[40:43], v[212:215], v[204:207], v[40:43]
	v_mfma_f32_16x16x32_bf16 v[36:39], v[246:249], v[204:207], v[36:39]
	s_mov_b32 m0, s48
	s_barrier
	ds_read_b128 v[148:151], v240 offset:49152
	ds_read_b128 v[152:155], v240 offset:50176
	ds_read_b128 v[156:159], v240 offset:51200
	ds_read_b128 v[160:163], v240 offset:52224
	ds_read_b128 v[164:167], v240 offset:53248
	ds_read_b128 v[168:171], v240 offset:54272
	ds_read_b128 v[172:175], v240 offset:55296
	s_add_u32 s98, s46, 0x80
	s_addc_u32 s99, s47, 0
	global_load_lds_dwordx4 v0, s[98:99]
	s_mov_b32 m0, s50
	ds_read_b128 v[204:207], v240 offset:56320
	global_load_lds_dwordx4 v178, s[98:99]
	s_barrier
	s_waitcnt lgkmcnt(0)
	v_mfma_f32_16x16x32_bf16 v[96:99], v[132:135], v[148:151], v[96:99]
	v_mfma_f32_16x16x32_bf16 v[92:95], v[140:143], v[148:151], v[92:95]
	v_mfma_f32_16x16x32_bf16 v[88:91], v[132:135], v[156:159], v[88:91]
	v_mfma_f32_16x16x32_bf16 v[84:87], v[140:143], v[156:159], v[84:87]
	v_mfma_f32_16x16x32_bf16 v[80:83], v[132:135], v[164:167], v[80:83]
	v_mfma_f32_16x16x32_bf16 v[76:79], v[140:143], v[164:167], v[76:79]
	v_mfma_f32_16x16x32_bf16 v[72:75], v[132:135], v[172:175], v[72:75]
	v_mfma_f32_16x16x32_bf16 v[68:71], v[140:143], v[172:175], v[68:71]
	v_mfma_f32_16x16x32_bf16 v[96:99], v[136:139], v[152:155], v[96:99]
	v_mfma_f32_16x16x32_bf16 v[92:95], v[144:147], v[152:155], v[92:95]
	v_mfma_f32_16x16x32_bf16 v[88:91], v[136:139], v[160:163], v[88:91]
	v_mfma_f32_16x16x32_bf16 v[84:87], v[144:147], v[160:163], v[84:87]
	v_mfma_f32_16x16x32_bf16 v[80:83], v[136:139], v[168:171], v[80:83]
	v_mfma_f32_16x16x32_bf16 v[76:79], v[144:147], v[168:171], v[76:79]
	v_mfma_f32_16x16x32_bf16 v[72:75], v[136:139], v[204:207], v[72:75]
	v_mfma_f32_16x16x32_bf16 v[68:71], v[144:147], v[204:207], v[68:71]
	s_barrier
	s_add_i32 s23, s26, s61
	s_mov_b32 m0, s23
	s_add_u32 s24, s44, 0x40080
	s_addc_u32 s25, s45, 0
	global_load_lds_dwordx4 v176, s[24:25]
	s_add_i32 m0, s23, 0x2000
	s_waitcnt vmcnt(5)
	global_load_lds_dwordx4 v180, s[24:25]
	s_barrier
	v_mfma_f32_16x16x32_bf16 v[32:35], v[208:211], v[148:151], v[32:35]
	v_mfma_f32_16x16x32_bf16 v[28:31], v[242:245], v[148:151], v[28:31]
	v_mfma_f32_16x16x32_bf16 v[24:27], v[208:211], v[156:159], v[24:27]
	v_mfma_f32_16x16x32_bf16 v[20:23], v[242:245], v[156:159], v[20:23]
	v_mfma_f32_16x16x32_bf16 v[16:19], v[208:211], v[164:167], v[16:19]
	v_mfma_f32_16x16x32_bf16 v[12:15], v[242:245], v[164:167], v[12:15]
	v_mfma_f32_16x16x32_bf16 v[8:11], v[208:211], v[172:175], v[8:11]
	v_mfma_f32_16x16x32_bf16 v[4:7], v[242:245], v[172:175], v[4:7]
	v_mfma_f32_16x16x32_bf16 v[32:35], v[212:215], v[152:155], v[32:35]
	v_mfma_f32_16x16x32_bf16 v[28:31], v[246:249], v[152:155], v[28:31]
	v_mfma_f32_16x16x32_bf16 v[24:27], v[212:215], v[160:163], v[24:27]
	v_mfma_f32_16x16x32_bf16 v[20:23], v[246:249], v[160:163], v[20:23]
	v_mfma_f32_16x16x32_bf16 v[16:19], v[212:215], v[168:171], v[16:19]
	v_mfma_f32_16x16x32_bf16 v[12:15], v[246:249], v[168:171], v[12:15]
	v_mfma_f32_16x16x32_bf16 v[8:11], v[212:215], v[204:207], v[8:11]
	v_mfma_f32_16x16x32_bf16 v[4:7], v[246:249], v[204:207], v[4:7]
	s_add_i32 s22, s22, 2
	s_add_u32 s0, s0, 0x100
	s_addc_u32 s1, s1, 0
	s_add_u32 s20, s20, 0x100
	s_addc_u32 s21, s21, 0
	s_cmp_gt_u32 s22, 13
	s_barrier
	s_cbranch_scc0 .LBB0_242
.Lpeel_out_242:
	v_readlane_b32 s98, v255, 3
	v_readlane_b32 s99, v255, 4
	s_nop 0
	s_cmp_eq_u64 s[98:99], 0
	s_cbranch_scc1 .Lep_a_242
	s_barrier
.Lep_a_242:
	s_add_i32 s0, s66, -8
	s_cmp_lt_u32 s0, 12
	s_mov_b64 s[0:1], -1
	s_cbranch_scc1 .LBB0_266
	s_cmp_gt_i32 s66, 33
	s_cselect_b64 s[64:65], -1, 0
	s_lshl_b32 s0, s66, 8
	s_lshl_b32 s53, s60, 8
	s_add_i32 s1, s0, 0xffffee00
	s_cmp_lt_i32 s66, 26
	v_cndmask_b32_e64 v2, 0, 1, s[80:81]
	s_cselect_b32 s62, s0, s1
	s_mov_b64 s[0:1], -1
	s_and_b64 vcc, exec, s[64:65]
	v_cmp_ne_u32_e64 s[44:45], 1, v2
	s_cbranch_vccz .LBB0_248
	s_and_b64 vcc, exec, s[44:45]
	s_cbranch_vccnz .LBB0_247
	v_add_u32_e32 v132, s53, v185
	v_ashrrev_i32_e32 v133, 31, v132
	v_lshlrev_b64 v[140:141], 7, v[132:133]
	global_load_dwordx4 v[132:135], v[188:189], off offset:16
	global_load_dwordx4 v[136:139], v[188:189], off
	s_mov_b32 s3, 0xbfb8aa3b
	s_mov_b32 s2, 0x800000
	s_mov_b32 s5, 0x3f317217
	s_mov_b32 s6, 0x7f800000
	s_waitcnt vmcnt(0)
	v_add_f32_e32 v147, v126, v134
	v_add_f32_e32 v2, v128, v136
	v_max_f32_e32 v142, 0, v2
	v_mul_f32_e64 v2, |v2|, s3
	v_exp_f32_e32 v2, v2
	v_add_f32_e32 v136, v124, v132
	v_add_f32_e32 v149, v127, v135
	v_add_f32_e32 v2, 1.0, v2
	v_cmp_gt_f32_e32 vcc, s2, v2
	s_nop 1
	v_cndmask_b32_e64 v132, 0, 32, vcc
	v_ldexp_f32 v2, v2, v132
	v_log_f32_e32 v2, v2
	s_nop 0
	v_mul_f32_e32 v132, 0x3f317217, v2
	v_fma_f32 v132, v2, s5, -v132
	v_fmac_f32_e32 v132, 0x3377d1cf, v2
	v_fmac_f32_e32 v132, 0x3f317217, v2
	v_cmp_lt_f32_e64 s[0:1], |v2|, s6
	s_nop 1
	v_cndmask_b32_e64 v2, v2, v132, s[0:1]
	v_cndmask_b32_e32 v132, 0, v228, vcc
	v_sub_f32_e32 v144, v2, v132
	v_mul_f32_e64 v2, |v136|, s3
	v_exp_f32_e32 v2, v2
	v_max_f32_e32 v132, 0, v136
	v_add_f32_e32 v2, 1.0, v2
	v_cmp_gt_f32_e32 vcc, s2, v2
	s_nop 1
	v_cndmask_b32_e64 v136, 0, 32, vcc
	v_ldexp_f32 v2, v2, v136
	v_log_f32_e32 v2, v2
	s_nop 0
	v_mul_f32_e32 v136, 0x3f317217, v2
	v_fma_f32 v136, v2, s5, -v136
	v_fmac_f32_e32 v136, 0x3377d1cf, v2
	v_fmac_f32_e32 v136, 0x3f317217, v2
	v_cmp_lt_f32_e64 s[0:1], |v2|, s6
	s_nop 1
	v_cndmask_b32_e64 v2, v2, v136, s[0:1]
	v_cndmask_b32_e32 v136, 0, v228, vcc
	v_sub_f32_e32 v136, v2, v136
	v_add_f32_e32 v2, v129, v137
	v_max_f32_e32 v143, 0, v2
	v_mul_f32_e64 v2, |v2|, s3
	v_exp_f32_e32 v2, v2
	v_add_f32_e32 v137, v125, v133
	v_add_f32_e32 v2, 1.0, v2
	v_cmp_gt_f32_e32 vcc, s2, v2
	s_nop 1
	v_cndmask_b32_e64 v133, 0, 32, vcc
	v_ldexp_f32 v2, v2, v133
	v_log_f32_e32 v2, v2
	s_nop 0
	v_mul_f32_e32 v133, 0x3f317217, v2
	v_fma_f32 v133, v2, s5, -v133
	v_fmac_f32_e32 v133, 0x3377d1cf, v2
	v_fmac_f32_e32 v133, 0x3f317217, v2
	v_cmp_lt_f32_e64 s[0:1], |v2|, s6
	s_nop 1
	v_cndmask_b32_e64 v2, v2, v133, s[0:1]
	v_cndmask_b32_e32 v133, 0, v228, vcc
	v_sub_f32_e32 v145, v2, v133
	v_mul_f32_e64 v2, |v137|, s3
	v_exp_f32_e32 v2, v2
	v_max_f32_e32 v133, 0, v137
	v_pk_add_f32 v[142:143], v[142:143], v[144:145]
	v_add_f32_e32 v2, 1.0, v2
	v_cmp_gt_f32_e32 vcc, s2, v2
	s_nop 1
	v_cndmask_b32_e64 v137, 0, 32, vcc
	v_ldexp_f32 v2, v2, v137
	v_log_f32_e32 v2, v2
	s_nop 0
	v_mul_f32_e32 v137, 0x3f317217, v2
	v_fma_f32 v137, v2, s5, -v137
	v_fmac_f32_e32 v137, 0x3377d1cf, v2
	v_fmac_f32_e32 v137, 0x3f317217, v2
	v_cmp_lt_f32_e64 s[0:1], |v2|, s6
	s_nop 1
	v_cndmask_b32_e64 v2, v2, v137, s[0:1]
	v_cndmask_b32_e32 v137, 0, v228, vcc
	v_sub_f32_e32 v137, v2, v137
	v_add_f32_e32 v2, v130, v138
	v_max_f32_e32 v138, 0, v2
	v_mul_f32_e64 v2, |v2|, s3
	v_exp_f32_e32 v2, v2
	v_pk_add_f32 v[132:133], v[132:133], v[136:137]
	v_lshl_add_u64 v[136:137], v[190:191], 0, v[140:141]
	v_add_f32_e32 v2, 1.0, v2
	v_cmp_gt_f32_e32 vcc, s2, v2
	s_nop 1
	v_cndmask_b32_e64 v134, 0, 32, vcc
	v_ldexp_f32 v2, v2, v134
	v_log_f32_e32 v2, v2
	s_nop 0
	v_mul_f32_e32 v134, 0x3f317217, v2
	v_fma_f32 v134, v2, s5, -v134
	v_fmac_f32_e32 v134, 0x3377d1cf, v2
	v_fmac_f32_e32 v134, 0x3f317217, v2
	v_cmp_lt_f32_e64 s[0:1], |v2|, s6
	s_nop 1
	v_cndmask_b32_e64 v2, v2, v134, s[0:1]
	v_cndmask_b32_e32 v134, 0, v228, vcc
	v_sub_f32_e32 v146, v2, v134
	v_mul_f32_e64 v2, |v147|, s3
	v_exp_f32_e32 v2, v2
	v_max_f32_e32 v134, 0, v147
	v_add_f32_e32 v2, 1.0, v2
	v_cmp_gt_f32_e32 vcc, s2, v2
	s_nop 1
	v_cndmask_b32_e64 v147, 0, 32, vcc
	v_ldexp_f32 v2, v2, v147
	v_log_f32_e32 v2, v2
	s_nop 0
	v_mul_f32_e32 v147, 0x3f317217, v2
	v_fma_f32 v147, v2, s5, -v147
	v_fmac_f32_e32 v147, 0x3377d1cf, v2
	v_fmac_f32_e32 v147, 0x3f317217, v2
	v_cmp_lt_f32_e64 s[0:1], |v2|, s6
	s_nop 1
	v_cndmask_b32_e64 v2, v2, v147, s[0:1]
	v_cndmask_b32_e32 v147, 0, v228, vcc
	v_sub_f32_e32 v148, v2, v147
	v_add_f32_e32 v2, v131, v139
	v_max_f32_e32 v139, 0, v2
	v_mul_f32_e64 v2, |v2|, s3
	v_exp_f32_e32 v2, v2
	s_nop 0
	v_add_f32_e32 v2, 1.0, v2
	v_cmp_gt_f32_e32 vcc, s2, v2
	s_nop 1
	v_cndmask_b32_e64 v135, 0, 32, vcc
	v_ldexp_f32 v2, v2, v135
	v_log_f32_e32 v2, v2
	s_nop 0
	v_mul_f32_e32 v135, 0x3f317217, v2
	v_fma_f32 v135, v2, s5, -v135
	v_fmac_f32_e32 v135, 0x3377d1cf, v2
	v_fmac_f32_e32 v135, 0x3f317217, v2
	v_cmp_lt_f32_e64 s[0:1], |v2|, s6
	s_nop 1
	v_cndmask_b32_e64 v2, v2, v135, s[0:1]
	v_cndmask_b32_e32 v135, 0, v228, vcc
	v_sub_f32_e32 v147, v2, v135
	v_mul_f32_e64 v2, |v149|, s3
	v_exp_f32_e32 v2, v2
	v_pk_add_f32 v[144:145], v[138:139], v[146:147]
	v_max_f32_e32 v135, 0, v149
	v_add_f32_e32 v2, 1.0, v2
	v_cmp_gt_f32_e32 vcc, s2, v2
	s_nop 1
	v_cndmask_b32_e64 v138, 0, 32, vcc
	v_ldexp_f32 v2, v2, v138
	v_log_f32_e32 v2, v2
	s_nop 0
	v_mul_f32_e32 v138, 0x3f317217, v2
	v_fma_f32 v138, v2, s5, -v138
	v_fmac_f32_e32 v138, 0x3377d1cf, v2
	v_fmac_f32_e32 v138, 0x3f317217, v2
	v_cmp_lt_f32_e64 s[0:1], |v2|, s6
	s_nop 1
	v_cndmask_b32_e64 v2, v2, v138, s[0:1]
	v_cndmask_b32_e32 v138, 0, v228, vcc
	v_sub_f32_e32 v149, v2, v138
	v_pk_add_f32 v[134:135], v[134:135], v[148:149]
	global_store_dwordx4 v[136:137], v[142:145], off
	global_store_dwordx4 v[136:137], v[132:135], off offset:16
